# query up-projection epilogue: gain-table and rope-table loads issued up front and reused from registers; in-projection epilogue: row sum-of-squares loads for all four row groups issued together
# baseline (speedup 1.0000x reference)
; DI unsigned pk2(float a, float b) { f2_t v = {a, b}; return __builtin_bit_cast(unsigned, __builtin_convertvector(v, bf2_t)); }
; DI void epi_inproj(f32x16 (&acc)[4][2], int m0, int n0, const Params& p, char* lds) {
;     ...
;   for (int mt = 0; mt < 4; ++mt) {
;     const int row = m0 + wr * 128 + mt * 32 + r;
;     const float rs = rsqrtf(sum_parts16(p.ssp + (size_t)row * 16) * (1.f / 1024.f) + EPS);
;     float sq = 0.f;
; #pragma unroll
;     for (int nt = 0; nt < 2; ++nt)
; #pragma unroll
;       for (int g = 0; g < 4; ++g) {
;         const float v0 = acc[mt][nt][4 * g] * rs, v1 = acc[mt][nt][4 * g + 1] * rs, v2 = acc[mt][nt][4 * g + 2] * rs, v3 = acc[mt][nt][4 * g + 3] * rs;
;         sq += v0 * v0 + v1 * v1 + v2 * v2 + v3 * v3;
;         u32x2 w; w.x = pk2(v0, v1); w.y = pk2(v2, v3); *(u32x2*)(st + (mt * 32 + r) * 72 + nt * 32 + 8 * g + 4 * h) = w;
;       }
;     sq += __shfl_xor(sq, 32);
.LBB0_679:
	v_mov_b32_e32 v136, v227
	s_movk_i32 s1, 0x4800
	v_lshrrev_b32_e32 v0, 6, v136
	v_and_b32_e32 v141, 31, v136
	v_mul_lo_u32 v135, v0, s1
	v_ashrrev_i32_e32 v0, 1, v136
	v_and_b32_e32 v137, 0xffffff80, v0
	v_or_b32_e32 v0, s35, v141
	v_add_u32_e32 v132, v0, v137
	v_ashrrev_i32_e32 v133, 31, v132
	v_lshlrev_b64 v[142:143], 6, v[132:133]
	v_lshl_add_u64 v[154:155], s[70:71], 0, v[142:143]
	v_mov_b32_e32 v208, v154
	v_mov_b32_e32 v209, v155
	global_load_dwordx4 v[142:145], v[154:155], off offset:48
	global_load_dwordx4 v[146:149], v[154:155], off offset:32
	global_load_dwordx4 v[150:153], v[154:155], off offset:16
	s_nop 0
	global_load_dwordx4 v[154:157], v[154:155], off
	global_load_dwordx4 v[160:163], v[208:209], off offset:2096
	global_load_dwordx4 v[164:167], v[208:209], off offset:2080
	global_load_dwordx4 v[168:171], v[208:209], off offset:2064
	global_load_dwordx4 v[172:175], v[208:209], off offset:2048
	s_mov_b64 s[96:97], 0x1000
	v_lshl_add_u64 v[210:211], v[208:209], 0, s[96:97]
	global_load_dwordx4 v[176:179], v[210:211], off offset:48
	global_load_dwordx4 v[180:183], v[210:211], off offset:32
	global_load_dwordx4 v[184:187], v[210:211], off offset:16
	global_load_dwordx4 v[188:191], v[210:211], off
	global_load_dwordx4 v[192:195], v[210:211], off offset:2096
	global_load_dwordx4 v[196:199], v[210:211], off offset:2080
	global_load_dwordx4 v[200:203], v[210:211], off offset:2064
	global_load_dwordx4 v[204:207], v[210:211], off offset:2048
	v_lshrrev_b32_e32 v0, 2, v136
	v_and_or_b32 v140, v0, 8, v135
	v_and_b32_e32 v130, 64, v239
	v_xor_b32_e32 v0, 32, v239
	v_add_u32_e32 v130, 64, v130
	v_cmp_lt_i32_e32 vcc, v0, v130
	v_and_b32_e32 v134, 63, v136
	v_cmp_gt_u32_e64 s[36:37], 32, v134
	v_cndmask_b32_e32 v0, v239, v0, vcc
	v_lshlrev_b32_e32 v139, 2, v0
	v_and_b32_e32 v0, 0xc0, v136
	v_or_b32_e32 v138, s0, v0
	v_ashrrev_i32_e32 v0, 6, v138
	v_cmp_lt_i32_e64 s[0:1], 5, v0
	v_cmp_gt_u32_e32 vcc, 10, v0
	v_ashrrev_i32_e32 v131, 31, v0
	v_mov_b32_e32 v130, v0
	s_waitcnt vmcnt(14)
	v_add_f32_e32 v146, v146, v147
	v_add_f32_e32 v148, v148, v149
	s_waitcnt vmcnt(12)
	v_mov_b32_e32 v158, v155
	v_mov_b32_e32 v159, v156
	v_mov_b32_e32 v155, v157
	v_mov_b32_e32 v156, v151
	v_mov_b32_e32 v157, v152
	v_mov_b32_e32 v151, v153
	v_pk_add_f32 v[154:155], v[158:159], v[154:155]
	v_pk_add_f32 v[150:151], v[156:157], v[150:151]
	v_pk_add_f32 v[154:155], v[154:155], v[154:155] op_sel:[0,1] op_sel_hi:[1,0]
	v_pk_add_f32 v[150:151], v[150:151], v[150:151] op_sel:[0,1] op_sel_hi:[1,0]
	v_mov_b32_e32 v155, v142
	v_mov_b32_e32 v151, v143
	v_mov_b32_e32 v147, v144
	v_mov_b32_e32 v149, v145
	v_pk_add_f32 v[142:143], v[154:155], v[150:151]
	v_pk_add_f32 v[144:145], v[146:147], v[148:149]
	s_nop 0
	v_pk_add_f32 v[142:143], v[142:143], v[144:145]
	s_nop 0
	v_add_f32_e32 v142, v142, v143
	v_fmamk_f32 v142, v142, 0x3a800000, v226
	v_cmp_gt_f32_e64 s[38:39], s72, v142
	v_mul_f32_e32 v143, 0x4b800000, v142
	s_nop 0
	v_cndmask_b32_e64 v142, v142, v143, s[38:39]
	v_rsq_f32_e32 v142, v142
	s_nop 0
	v_mul_f32_e32 v143, 0x45800000, v142
	v_cndmask_b32_e64 v142, v142, v143, s[38:39]
	v_mad_u32_u24 v143, v141, s54, v140
	v_pk_mul_f32 v[144:145], v[114:115], v[142:143] op_sel_hi:[1,0]
	v_pk_mul_f32 v[146:147], v[116:117], v[142:143] op_sel_hi:[1,0]
	v_pk_mul_f32 v[118:119], v[118:119], v[142:143] op_sel_hi:[1,0]
	v_pk_mul_f32 v[120:121], v[120:121], v[142:143] op_sel_hi:[1,0]
	v_pk_mul_f32 v[116:117], v[144:145], v[144:145]
	v_pk_mul_f32 v[114:115], v[146:147], v[146:147]
	v_cvt_pk_bf16_f32 v144, v144, v145
	v_cvt_pk_bf16_f32 v145, v146, v147
	v_pk_mul_f32 v[146:147], v[118:119], v[118:119]
	v_cvt_pk_bf16_f32 v118, v118, v119
	v_cvt_pk_bf16_f32 v119, v120, v121
	v_pk_mul_f32 v[148:149], v[120:121], v[120:121]
	ds_write2_b64 v143, v[144:145], v[118:119] offset1:2
	v_pk_mul_f32 v[118:119], v[122:123], v[142:143] op_sel_hi:[1,0]
	v_pk_mul_f32 v[120:121], v[124:125], v[142:143] op_sel_hi:[1,0]
	v_pk_mul_f32 v[122:123], v[118:119], v[118:119]
	v_pk_mul_f32 v[124:125], v[120:121], v[120:121]
	v_cvt_pk_bf16_f32 v118, v118, v119
	v_cvt_pk_bf16_f32 v119, v120, v121
	v_pk_mul_f32 v[120:121], v[126:127], v[142:143] op_sel_hi:[1,0]
	v_pk_mul_f32 v[126:127], v[128:129], v[142:143] op_sel_hi:[1,0]
	v_pk_mul_f32 v[128:129], v[120:121], v[120:121]
	v_cvt_pk_bf16_f32 v120, v120, v121
	v_cvt_pk_bf16_f32 v121, v126, v127
	v_pk_mul_f32 v[98:99], v[98:99], v[142:143] op_sel_hi:[1,0]
	v_pk_mul_f32 v[100:101], v[100:101], v[142:143] op_sel_hi:[1,0]
	ds_write2_b64 v143, v[118:119], v[120:121] offset0:4 offset1:6
	v_pk_mul_f32 v[118:119], v[98:99], v[98:99]
	v_pk_mul_f32 v[120:121], v[100:101], v[100:101]
	v_cvt_pk_bf16_f32 v98, v98, v99
	v_cvt_pk_bf16_f32 v99, v100, v101
	v_pk_mul_f32 v[100:101], v[102:103], v[142:143] op_sel_hi:[1,0]
	v_pk_mul_f32 v[102:103], v[104:105], v[142:143] op_sel_hi:[1,0]
	v_pk_mul_f32 v[104:105], v[100:101], v[100:101]
	v_cvt_pk_bf16_f32 v100, v100, v101
	v_cvt_pk_bf16_f32 v101, v102, v103
	ds_write2_b64 v143, v[98:99], v[100:101] offset0:8 offset1:10
	v_pk_mul_f32 v[100:101], v[108:109], v[142:143] op_sel_hi:[1,0]
	v_add_f32_e32 v116, v116, v117
	v_pk_mul_f32 v[98:99], v[106:107], v[142:143] op_sel_hi:[1,0]
	v_pk_mul_f32 v[106:107], v[100:101], v[100:101]
	v_cvt_pk_bf16_f32 v109, v100, v101
	v_pk_mul_f32 v[100:101], v[110:111], v[142:143] op_sel_hi:[1,0]
	v_pk_mul_f32 v[110:111], v[112:113], v[142:143] op_sel_hi:[1,0]
	v_add_f32_e32 v142, v146, v147
	v_add_f32_e32 v114, v114, v116
	v_add_f32_e32 v142, v148, v142
	v_add_f32_e32 v114, v115, v114
	v_add_f32_e32 v115, v122, v123
	v_add_f32_e32 v142, v149, v142
	v_add_f32_e32 v115, v124, v115
	v_add_f32_e32 v114, v114, v142
	v_add_f32_e32 v115, v125, v115
	v_pk_mul_f32 v[144:145], v[126:127], v[126:127]
	v_add_f32_e32 v114, v115, v114
	v_add_f32_e32 v115, v128, v129
	v_add_f32_e32 v115, v144, v115
	v_add_f32_e32 v115, v145, v115
	v_add_f32_e32 v114, v115, v114
	v_add_f32_e32 v115, v118, v119
	v_pk_mul_f32 v[126:127], v[102:103], v[102:103]
	v_pk_mul_f32 v[102:103], v[98:99], v[98:99]
	v_add_f32_e32 v115, v120, v115
	v_add_f32_e32 v104, v104, v105
	v_cvt_pk_bf16_f32 v108, v98, v99
	v_pk_mul_f32 v[98:99], v[100:101], v[100:101]
	v_add_f32_e32 v115, v121, v115
	v_add_f32_e32 v104, v126, v104
	v_add_f32_e32 v102, v102, v103
	v_pk_mul_f32 v[112:113], v[110:111], v[110:111]
	v_add_f32_e32 v114, v115, v114
	v_add_f32_e32 v104, v127, v104
	v_add_f32_e32 v102, v106, v102
	v_add_f32_e32 v98, v98, v99
	v_add_f32_e32 v104, v104, v114
	v_add_f32_e32 v102, v107, v102
	v_add_f32_e32 v98, v112, v98
	v_add_f32_e32 v102, v102, v104
	v_add_f32_e32 v98, v113, v98
	v_add_f32_e32 v98, v98, v102
	ds_bpermute_b32 v99, v139, v98
	v_cvt_pk_bf16_f32 v100, v100, v101
	v_cvt_pk_bf16_f32 v101, v110, v111
	ds_write2_b64 v143, v[108:109], v[100:101] offset0:12 offset1:14
	s_and_saveexec_b64 s[2:3], s[36:37]
	s_cbranch_execz .LBB0_686
; DI void epi_inproj(f32x16 (&acc)[4][2], int m0, int n0, const Params& p, char* lds) {
;     ...
;     sq += __shfl_xor(sq, 32);
;     const int c64 = (n0 + wc * 64) >> 6;
;     if (h == 0) { if (c64 < 6) p.ssq[(size_t)row * 8 + c64] = sq; else if (c64 < 10) p.sskv[(size_t)row * 4 + (c64 - 6)] = sq; }
	s_waitcnt lgkmcnt(1)
	v_add_f32_e32 v98, v98, v99
	s_and_saveexec_b64 s[4:5], s[0:1]
	s_xor_b64 s[4:5], exec, s[4:5]
	s_cbranch_execz .LBB0_684
	s_and_saveexec_b64 s[6:7], vcc
	s_cbranch_execz .LBB0_683
	v_lshl_add_u64 v[100:101], v[132:133], 4, s[26:27]
	v_lshl_add_u64 v[100:101], v[0:1], 2, v[100:101]
	global_store_dword v[100:101], v98, off offset:-24

; DI unsigned pk2(float a, float b) { f2_t v = {a, b}; return __builtin_bit_cast(unsigned, __builtin_convertvector(v, bf2_t)); }
; DI void epi_inproj(f32x16 (&acc)[4][2], int m0, int n0, const Params& p, char* lds) {
;     ...
;   for (int mt = 0; mt < 4; ++mt) {
;     const int row = m0 + wr * 128 + mt * 32 + r;
;     const float rs = rsqrtf(sum_parts16(p.ssp + (size_t)row * 16) * (1.f / 1024.f) + EPS);
;     float sq = 0.f;
; #pragma unroll
;     for (int nt = 0; nt < 2; ++nt)
; #pragma unroll
;       for (int g = 0; g < 4; ++g) {
;         const float v0 = acc[mt][nt][4 * g] * rs, v1 = acc[mt][nt][4 * g + 1] * rs, v2 = acc[mt][nt][4 * g + 2] * rs, v3 = acc[mt][nt][4 * g + 3] * rs;
;         sq += v0 * v0 + v1 * v1 + v2 * v2 + v3 * v3;
;         u32x2 w; w.x = pk2(v0, v1); w.y = pk2(v2, v3); *(u32x2*)(st + (mt * 32 + r) * 72 + nt * 32 + 8 * g + 4 * h) = w;
;       }
;     sq += __shfl_xor(sq, 32);
;     const int c64 = (n0 + wc * 64) >> 6;
;     if (h == 0) { if (c64 < 6) p.ssq[(size_t)row * 8 + c64] = sq; else if (c64 < 10) p.sskv[(size_t)row * 4 + (c64 - 6)] = sq; }
.LBB0_686:
	s_or_b64 exec, exec, s[2:3]
	v_or_b32_e32 v98, 32, v132
	s_waitcnt lgkmcnt(1)
	v_ashrrev_i32_e32 v99, 31, v98
	v_lshlrev_b64 v[100:101], 6, v[98:99]
	v_lshl_add_u64 v[112:113], s[70:71], 0, v[100:101]
	s_waitcnt vmcnt(8)
	v_mov_b64_e32 v[100:101], v[160:161]
	v_mov_b64_e32 v[102:103], v[162:163]
	v_mov_b64_e32 v[104:105], v[164:165]
	v_mov_b64_e32 v[106:107], v[166:167]
	v_mov_b64_e32 v[108:109], v[168:169]
	v_mov_b64_e32 v[110:111], v[170:171]
	v_mov_b64_e32 v[112:113], v[172:173]
	v_mov_b64_e32 v[114:115], v[174:175]
	v_mul_u32_u24_e32 v118, 0x90, v141
	v_add_f32_e32 v104, v104, v105
	v_add_f32_e32 v106, v106, v107
	v_mov_b32_e32 v116, v113
	v_mov_b32_e32 v117, v114
	v_mov_b32_e32 v113, v115
	v_mov_b32_e32 v114, v109
	v_mov_b32_e32 v115, v110
	v_mov_b32_e32 v109, v111
	v_pk_add_f32 v[112:113], v[116:117], v[112:113]
	v_pk_add_f32 v[108:109], v[114:115], v[108:109]
	v_pk_add_f32 v[112:113], v[112:113], v[112:113] op_sel:[0,1] op_sel_hi:[1,0]
	v_pk_add_f32 v[108:109], v[108:109], v[108:109] op_sel:[0,1] op_sel_hi:[1,0]
	v_mov_b32_e32 v113, v100
	v_mov_b32_e32 v109, v101
	v_mov_b32_e32 v105, v102
	v_mov_b32_e32 v107, v103
	v_pk_add_f32 v[100:101], v[112:113], v[108:109]
	v_pk_add_f32 v[102:103], v[104:105], v[106:107]
	s_nop 0
	v_pk_add_f32 v[100:101], v[100:101], v[102:103]
	s_nop 0
	v_add_f32_e32 v100, v100, v101
	v_fmamk_f32 v100, v100, 0x3a800000, v226
	v_cmp_gt_f32_e64 s[38:39], s72, v100
	v_mul_f32_e32 v101, 0x4b800000, v100
	s_nop 0
	v_cndmask_b32_e64 v100, v100, v101, s[38:39]
	v_rsq_f32_e32 v100, v100
	s_nop 0
	v_mul_f32_e32 v101, 0x45800000, v100
	v_cndmask_b32_e64 v102, v100, v101, s[38:39]
	v_pk_mul_f32 v[100:101], v[82:83], v[102:103] op_sel_hi:[1,0]
	v_pk_mul_f32 v[104:105], v[84:85], v[102:103] op_sel_hi:[1,0]
	v_pk_mul_f32 v[84:85], v[100:101], v[100:101]
	v_pk_mul_f32 v[82:83], v[104:105], v[104:105]
	v_cvt_pk_bf16_f32 v106, v100, v101
	v_cvt_pk_bf16_f32 v107, v104, v105
	v_add_u32_e32 v100, v140, v118
	v_pk_mul_f32 v[104:105], v[86:87], v[102:103] op_sel_hi:[1,0]
	v_pk_mul_f32 v[108:109], v[88:89], v[102:103] op_sel_hi:[1,0]
	v_pk_mul_f32 v[88:89], v[104:105], v[104:105]
	v_cvt_pk_bf16_f32 v104, v104, v105
	v_cvt_pk_bf16_f32 v105, v108, v109
	v_add_u32_e32 v101, 0x1000, v100
	v_pk_mul_f32 v[90:91], v[90:91], v[102:103] op_sel_hi:[1,0]
	v_add_f32_e32 v84, v84, v85
	v_pk_mul_f32 v[86:87], v[108:109], v[108:109]
	ds_write2_b64 v101, v[106:107], v[104:105] offset0:64 offset1:66
	v_pk_mul_f32 v[92:93], v[92:93], v[102:103] op_sel_hi:[1,0]
	v_pk_mul_f32 v[104:105], v[90:91], v[90:91]
	v_add_f32_e32 v88, v88, v89
	v_add_f32_e32 v82, v82, v84
	v_pk_mul_f32 v[106:107], v[92:93], v[92:93]
	v_add_f32_e32 v86, v86, v88
	v_add_f32_e32 v82, v83, v82
	v_add_f32_e32 v83, v104, v105
	v_cvt_pk_bf16_f32 v90, v90, v91
	v_cvt_pk_bf16_f32 v91, v92, v93
	v_pk_mul_f32 v[92:93], v[94:95], v[102:103] op_sel_hi:[1,0]
	v_add_f32_e32 v86, v87, v86
	v_add_f32_e32 v83, v106, v83
	v_pk_mul_f32 v[94:95], v[96:97], v[102:103] op_sel_hi:[1,0]
	v_pk_mul_f32 v[96:97], v[92:93], v[92:93]
	v_add_f32_e32 v82, v82, v86
	v_add_f32_e32 v83, v107, v83
	v_pk_mul_f32 v[108:109], v[94:95], v[94:95]
	v_cvt_pk_bf16_f32 v92, v92, v93
	v_cvt_pk_bf16_f32 v93, v94, v95
	v_pk_mul_f32 v[66:67], v[66:67], v[102:103] op_sel_hi:[1,0]
	v_pk_mul_f32 v[68:69], v[68:69], v[102:103] op_sel_hi:[1,0]
	v_add_f32_e32 v82, v83, v82
	v_add_f32_e32 v83, v96, v97
	ds_write2_b64 v101, v[90:91], v[92:93] offset0:68 offset1:70
	v_pk_mul_f32 v[90:91], v[66:67], v[66:67]
	v_pk_mul_f32 v[92:93], v[68:69], v[68:69]
	v_cvt_pk_bf16_f32 v66, v66, v67
	v_cvt_pk_bf16_f32 v67, v68, v69
	v_pk_mul_f32 v[68:69], v[70:71], v[102:103] op_sel_hi:[1,0]
	v_pk_mul_f32 v[70:71], v[72:73], v[102:103] op_sel_hi:[1,0]
	v_add_f32_e32 v83, v108, v83
	v_pk_mul_f32 v[72:73], v[68:69], v[68:69]
	v_cvt_pk_bf16_f32 v68, v68, v69
	v_cvt_pk_bf16_f32 v69, v70, v71
	v_add_f32_e32 v83, v109, v83
	ds_write2_b64 v101, v[66:67], v[68:69] offset0:72 offset1:74
	v_pk_mul_f32 v[66:67], v[74:75], v[102:103] op_sel_hi:[1,0]
	v_pk_mul_f32 v[68:69], v[76:77], v[102:103] op_sel_hi:[1,0]
	v_add_f32_e32 v82, v83, v82
	v_add_f32_e32 v83, v90, v91
	v_pk_mul_f32 v[94:95], v[70:71], v[70:71]
	v_pk_mul_f32 v[70:71], v[66:67], v[66:67]
	v_pk_mul_f32 v[74:75], v[68:69], v[68:69]
	v_cvt_pk_bf16_f32 v77, v68, v69
	v_pk_mul_f32 v[68:69], v[78:79], v[102:103] op_sel_hi:[1,0]
	v_add_f32_e32 v83, v92, v83
	v_add_f32_e32 v72, v72, v73
	v_cvt_pk_bf16_f32 v76, v66, v67
	v_pk_mul_f32 v[78:79], v[80:81], v[102:103] op_sel_hi:[1,0]
	v_pk_mul_f32 v[66:67], v[68:69], v[68:69]
	v_add_f32_e32 v83, v93, v83
	v_add_f32_e32 v72, v94, v72
	v_add_f32_e32 v70, v70, v71
	v_pk_mul_f32 v[80:81], v[78:79], v[78:79]
	v_add_f32_e32 v82, v83, v82
	v_add_f32_e32 v72, v95, v72
	v_add_f32_e32 v70, v74, v70
	v_add_f32_e32 v66, v66, v67
	v_add_f32_e32 v72, v72, v82
	v_add_f32_e32 v70, v75, v70
	v_add_f32_e32 v66, v80, v66
	v_add_f32_e32 v70, v70, v72
	v_add_f32_e32 v66, v81, v66
	v_add_f32_e32 v66, v66, v70
	ds_bpermute_b32 v67, v139, v66
	v_cvt_pk_bf16_f32 v68, v68, v69
	v_cvt_pk_bf16_f32 v69, v78, v79
	ds_write2_b64 v101, v[76:77], v[68:69] offset0:76 offset1:78
	s_and_saveexec_b64 s[2:3], s[36:37]
	s_cbranch_execz .LBB0_693
	s_waitcnt lgkmcnt(1)
	v_add_f32_e32 v66, v66, v67
	s_and_saveexec_b64 s[4:5], s[0:1]
	s_xor_b64 s[4:5], exec, s[4:5]
	s_cbranch_execz .LBB0_691
	s_and_saveexec_b64 s[6:7], vcc
	s_cbranch_execz .LBB0_690
	v_lshl_add_u64 v[68:69], v[98:99], 4, s[26:27]
	v_lshl_add_u64 v[68:69], v[0:1], 2, v[68:69]
	global_store_dword v[68:69], v66, off offset:-24

; DI unsigned pk2(float a, float b) { f2_t v = {a, b}; return __builtin_bit_cast(unsigned, __builtin_convertvector(v, bf2_t)); }
; DI void epi_inproj(f32x16 (&acc)[4][2], int m0, int n0, const Params& p, char* lds) {
;     ...
;   for (int mt = 0; mt < 4; ++mt) {
;     const int row = m0 + wr * 128 + mt * 32 + r;
;     const float rs = rsqrtf(sum_parts16(p.ssp + (size_t)row * 16) * (1.f / 1024.f) + EPS);
;     float sq = 0.f;
; #pragma unroll
;     for (int nt = 0; nt < 2; ++nt)
; #pragma unroll
;       for (int g = 0; g < 4; ++g) {
;         const float v0 = acc[mt][nt][4 * g] * rs, v1 = acc[mt][nt][4 * g + 1] * rs, v2 = acc[mt][nt][4 * g + 2] * rs, v3 = acc[mt][nt][4 * g + 3] * rs;
;         sq += v0 * v0 + v1 * v1 + v2 * v2 + v3 * v3;
;         u32x2 w; w.x = pk2(v0, v1); w.y = pk2(v2, v3); *(u32x2*)(st + (mt * 32 + r) * 72 + nt * 32 + 8 * g + 4 * h) = w;
;       }
;     sq += __shfl_xor(sq, 32);
;     const int c64 = (n0 + wc * 64) >> 6;
;     if (h == 0) { if (c64 < 6) p.ssq[(size_t)row * 8 + c64] = sq; else if (c64 < 10) p.sskv[(size_t)row * 4 + (c64 - 6)] = sq; }
.LBB0_693:
	s_or_b64 exec, exec, s[2:3]
	v_or_b32_e32 v66, 64, v132
	s_waitcnt lgkmcnt(1)
	v_ashrrev_i32_e32 v67, 31, v66
	v_lshlrev_b64 v[68:69], 6, v[66:67]
	v_lshl_add_u64 v[80:81], s[70:71], 0, v[68:69]
	s_waitcnt vmcnt(4)
	v_mov_b64_e32 v[68:69], v[176:177]
	v_mov_b64_e32 v[70:71], v[178:179]
	v_mov_b64_e32 v[72:73], v[180:181]
	v_mov_b64_e32 v[74:75], v[182:183]
	v_mov_b64_e32 v[76:77], v[184:185]
	v_mov_b64_e32 v[78:79], v[186:187]
	v_mov_b64_e32 v[80:81], v[188:189]
	v_mov_b64_e32 v[82:83], v[190:191]
	v_add_f32_e32 v72, v72, v73
	v_add_f32_e32 v74, v74, v75
	v_mov_b32_e32 v84, v81
	v_mov_b32_e32 v85, v82
	v_mov_b32_e32 v81, v83
	v_mov_b32_e32 v82, v77
	v_mov_b32_e32 v83, v78
	v_mov_b32_e32 v77, v79
	v_pk_add_f32 v[80:81], v[84:85], v[80:81]
	v_pk_add_f32 v[76:77], v[82:83], v[76:77]
	v_pk_add_f32 v[80:81], v[80:81], v[80:81] op_sel:[0,1] op_sel_hi:[1,0]
	v_pk_add_f32 v[76:77], v[76:77], v[76:77] op_sel:[0,1] op_sel_hi:[1,0]
	v_mov_b32_e32 v81, v68
	v_mov_b32_e32 v77, v69
	v_mov_b32_e32 v73, v70
	v_mov_b32_e32 v75, v71
	v_pk_add_f32 v[68:69], v[80:81], v[76:77]
	v_pk_add_f32 v[70:71], v[72:73], v[74:75]
	s_nop 0
	v_pk_add_f32 v[68:69], v[68:69], v[70:71]
	s_nop 0
	v_add_f32_e32 v68, v68, v69
	v_fmamk_f32 v68, v68, 0x3a800000, v226
	v_cmp_gt_f32_e64 s[38:39], s72, v68
	v_mul_f32_e32 v69, 0x4b800000, v68
	s_nop 0
	v_cndmask_b32_e64 v68, v68, v69, s[38:39]
	v_rsq_f32_e32 v68, v68
	s_nop 0
	v_mul_f32_e32 v69, 0x45800000, v68
	v_cndmask_b32_e64 v68, v68, v69, s[38:39]
	v_pk_mul_f32 v[70:71], v[50:51], v[68:69] op_sel_hi:[1,0]
	v_pk_mul_f32 v[72:73], v[52:53], v[68:69] op_sel_hi:[1,0]
	v_pk_mul_f32 v[52:53], v[70:71], v[70:71]
	v_pk_mul_f32 v[50:51], v[72:73], v[72:73]
	v_cvt_pk_bf16_f32 v70, v70, v71
	v_cvt_pk_bf16_f32 v71, v72, v73
	v_pk_mul_f32 v[72:73], v[54:55], v[68:69] op_sel_hi:[1,0]
	v_pk_mul_f32 v[74:75], v[56:57], v[68:69] op_sel_hi:[1,0]
	v_add_u32_e32 v69, 0x2000, v100
	v_pk_mul_f32 v[56:57], v[72:73], v[72:73]
	v_cvt_pk_bf16_f32 v72, v72, v73
	v_cvt_pk_bf16_f32 v73, v74, v75
	v_pk_mul_f32 v[58:59], v[58:59], v[68:69] op_sel_hi:[1,0]
	v_add_f32_e32 v52, v52, v53
	v_pk_mul_f32 v[54:55], v[74:75], v[74:75]
	ds_write2_b64 v69, v[70:71], v[72:73] offset0:128 offset1:130
	v_pk_mul_f32 v[60:61], v[60:61], v[68:69] op_sel_hi:[1,0]
	v_pk_mul_f32 v[70:71], v[58:59], v[58:59]
	v_add_f32_e32 v56, v56, v57
	v_add_f32_e32 v50, v50, v52
	v_pk_mul_f32 v[72:73], v[60:61], v[60:61]
	v_add_f32_e32 v54, v54, v56
	v_add_f32_e32 v50, v51, v50
	v_add_f32_e32 v51, v70, v71
	v_cvt_pk_bf16_f32 v58, v58, v59
	v_cvt_pk_bf16_f32 v59, v60, v61
	v_pk_mul_f32 v[60:61], v[62:63], v[68:69] op_sel_hi:[1,0]
	v_add_f32_e32 v54, v55, v54
	v_add_f32_e32 v51, v72, v51
	v_pk_mul_f32 v[62:63], v[64:65], v[68:69] op_sel_hi:[1,0]
	v_pk_mul_f32 v[64:65], v[60:61], v[60:61]
	v_add_f32_e32 v50, v50, v54
	v_add_f32_e32 v51, v73, v51
	v_pk_mul_f32 v[74:75], v[62:63], v[62:63]
	v_cvt_pk_bf16_f32 v60, v60, v61
	v_cvt_pk_bf16_f32 v61, v62, v63
	v_pk_mul_f32 v[34:35], v[34:35], v[68:69] op_sel_hi:[1,0]
	v_pk_mul_f32 v[36:37], v[36:37], v[68:69] op_sel_hi:[1,0]
	v_add_f32_e32 v50, v51, v50
	v_add_f32_e32 v51, v64, v65
	ds_write2_b64 v69, v[58:59], v[60:61] offset0:132 offset1:134
	v_pk_mul_f32 v[58:59], v[34:35], v[34:35]
	v_pk_mul_f32 v[60:61], v[36:37], v[36:37]
	v_cvt_pk_bf16_f32 v34, v34, v35
	v_cvt_pk_bf16_f32 v35, v36, v37
	v_pk_mul_f32 v[36:37], v[38:39], v[68:69] op_sel_hi:[1,0]
	v_pk_mul_f32 v[38:39], v[40:41], v[68:69] op_sel_hi:[1,0]
	v_add_f32_e32 v51, v74, v51
	v_pk_mul_f32 v[40:41], v[36:37], v[36:37]
	v_cvt_pk_bf16_f32 v36, v36, v37
	v_cvt_pk_bf16_f32 v37, v38, v39
	v_add_f32_e32 v51, v75, v51
	ds_write2_b64 v69, v[34:35], v[36:37] offset0:136 offset1:138
	v_pk_mul_f32 v[34:35], v[42:43], v[68:69] op_sel_hi:[1,0]
	v_pk_mul_f32 v[36:37], v[44:45], v[68:69] op_sel_hi:[1,0]
	v_add_f32_e32 v50, v51, v50
	v_add_f32_e32 v51, v58, v59
	v_pk_mul_f32 v[62:63], v[38:39], v[38:39]
	v_pk_mul_f32 v[38:39], v[34:35], v[34:35]
	v_pk_mul_f32 v[42:43], v[36:37], v[36:37]
	v_cvt_pk_bf16_f32 v45, v36, v37
	v_pk_mul_f32 v[36:37], v[46:47], v[68:69] op_sel_hi:[1,0]
	v_add_f32_e32 v51, v60, v51
	v_add_f32_e32 v40, v40, v41
	v_cvt_pk_bf16_f32 v44, v34, v35
	v_pk_mul_f32 v[46:47], v[48:49], v[68:69] op_sel_hi:[1,0]
	v_pk_mul_f32 v[34:35], v[36:37], v[36:37]
	v_add_f32_e32 v51, v61, v51
	v_add_f32_e32 v40, v62, v40
	v_add_f32_e32 v38, v38, v39
	v_pk_mul_f32 v[48:49], v[46:47], v[46:47]
	v_add_f32_e32 v50, v51, v50
	v_add_f32_e32 v40, v63, v40
	v_add_f32_e32 v38, v42, v38
	v_add_f32_e32 v34, v34, v35
	v_add_f32_e32 v40, v40, v50
	v_add_f32_e32 v38, v43, v38
	v_add_f32_e32 v34, v48, v34
	v_add_f32_e32 v38, v38, v40
	v_add_f32_e32 v34, v49, v34
	v_add_f32_e32 v34, v34, v38
	ds_bpermute_b32 v35, v139, v34
	v_cvt_pk_bf16_f32 v36, v36, v37
	v_cvt_pk_bf16_f32 v37, v46, v47
	ds_write2_b64 v69, v[44:45], v[36:37] offset0:140 offset1:142
	s_and_saveexec_b64 s[2:3], s[36:37]
	s_cbranch_execz .LBB0_700
	s_waitcnt lgkmcnt(1)
	v_add_f32_e32 v34, v34, v35
	s_and_saveexec_b64 s[4:5], s[0:1]
	s_xor_b64 s[4:5], exec, s[4:5]
	s_cbranch_execz .LBB0_698
	s_and_saveexec_b64 s[6:7], vcc
	s_cbranch_execz .LBB0_697
	v_lshl_add_u64 v[36:37], v[66:67], 4, s[26:27]
	v_lshl_add_u64 v[36:37], v[0:1], 2, v[36:37]
	global_store_dword v[36:37], v34, off offset:-24

; DI unsigned pk2(float a, float b) { f2_t v = {a, b}; return __builtin_bit_cast(unsigned, __builtin_convertvector(v, bf2_t)); }
; DI void epi_inproj(f32x16 (&acc)[4][2], int m0, int n0, const Params& p, char* lds) {
;     ...
;   for (int mt = 0; mt < 4; ++mt) {
;     const int row = m0 + wr * 128 + mt * 32 + r;
;     const float rs = rsqrtf(sum_parts16(p.ssp + (size_t)row * 16) * (1.f / 1024.f) + EPS);
;     float sq = 0.f;
; #pragma unroll
;     for (int nt = 0; nt < 2; ++nt)
; #pragma unroll
;       for (int g = 0; g < 4; ++g) {
;         const float v0 = acc[mt][nt][4 * g] * rs, v1 = acc[mt][nt][4 * g + 1] * rs, v2 = acc[mt][nt][4 * g + 2] * rs, v3 = acc[mt][nt][4 * g + 3] * rs;
;         sq += v0 * v0 + v1 * v1 + v2 * v2 + v3 * v3;
;         u32x2 w; w.x = pk2(v0, v1); w.y = pk2(v2, v3); *(u32x2*)(st + (mt * 32 + r) * 72 + nt * 32 + 8 * g + 4 * h) = w;
;       }
;     sq += __shfl_xor(sq, 32);
;     const int c64 = (n0 + wc * 64) >> 6;
;     if (h == 0) { if (c64 < 6) p.ssq[(size_t)row * 8 + c64] = sq; else if (c64 < 10) p.sskv[(size_t)row * 4 + (c64 - 6)] = sq; }
.LBB0_700:
	s_or_b64 exec, exec, s[2:3]
	v_or_b32_e32 v34, 0x60, v132
	s_waitcnt lgkmcnt(1)
	v_ashrrev_i32_e32 v35, 31, v34
	v_lshlrev_b64 v[36:37], 6, v[34:35]
	v_lshl_add_u64 v[48:49], s[70:71], 0, v[36:37]
	s_waitcnt vmcnt(0)
	v_mov_b64_e32 v[36:37], v[192:193]
	v_mov_b64_e32 v[38:39], v[194:195]
	v_mov_b64_e32 v[40:41], v[196:197]
	v_mov_b64_e32 v[42:43], v[198:199]
	v_mov_b64_e32 v[44:45], v[200:201]
	v_mov_b64_e32 v[46:47], v[202:203]
	v_mov_b64_e32 v[48:49], v[204:205]
	v_mov_b64_e32 v[50:51], v[206:207]
	v_add_f32_e32 v40, v40, v41
	v_add_f32_e32 v42, v42, v43
	v_mov_b32_e32 v52, v49
	v_mov_b32_e32 v53, v50
	v_mov_b32_e32 v49, v51
	v_mov_b32_e32 v50, v45
	v_mov_b32_e32 v51, v46
	v_mov_b32_e32 v45, v47
	v_pk_add_f32 v[48:49], v[52:53], v[48:49]
	v_pk_add_f32 v[44:45], v[50:51], v[44:45]
	v_pk_add_f32 v[48:49], v[48:49], v[48:49] op_sel:[0,1] op_sel_hi:[1,0]
	v_pk_add_f32 v[44:45], v[44:45], v[44:45] op_sel:[0,1] op_sel_hi:[1,0]
	v_mov_b32_e32 v49, v36
	v_mov_b32_e32 v45, v37
	v_mov_b32_e32 v41, v38
	v_mov_b32_e32 v43, v39
	v_pk_add_f32 v[36:37], v[48:49], v[44:45]
	v_pk_add_f32 v[38:39], v[40:41], v[42:43]
	s_nop 0
	v_pk_add_f32 v[36:37], v[36:37], v[38:39]
	s_nop 0
	v_add_f32_e32 v36, v36, v37
	v_fmamk_f32 v36, v36, 0x3a800000, v226
	v_cmp_gt_f32_e64 s[38:39], s72, v36
	v_mul_f32_e32 v37, 0x4b800000, v36
	s_nop 0
	v_cndmask_b32_e64 v36, v36, v37, s[38:39]
	v_rsq_f32_e32 v36, v36
	s_nop 0
	v_mul_f32_e32 v37, 0x45800000, v36
	v_cndmask_b32_e64 v36, v36, v37, s[38:39]
	v_pk_mul_f32 v[38:39], v[18:19], v[36:37] op_sel_hi:[1,0]
	v_pk_mul_f32 v[40:41], v[20:21], v[36:37] op_sel_hi:[1,0]
	v_pk_mul_f32 v[20:21], v[38:39], v[38:39]
	v_pk_mul_f32 v[18:19], v[40:41], v[40:41]
	v_cvt_pk_bf16_f32 v38, v38, v39
	v_cvt_pk_bf16_f32 v39, v40, v41
	v_pk_mul_f32 v[40:41], v[22:23], v[36:37] op_sel_hi:[1,0]
	v_pk_mul_f32 v[42:43], v[24:25], v[36:37] op_sel_hi:[1,0]
	v_add_u32_e32 v37, 0x3000, v100
	v_pk_mul_f32 v[24:25], v[40:41], v[40:41]
	v_cvt_pk_bf16_f32 v40, v40, v41
	v_cvt_pk_bf16_f32 v41, v42, v43
	v_pk_mul_f32 v[26:27], v[26:27], v[36:37] op_sel_hi:[1,0]
	v_add_f32_e32 v20, v20, v21
	v_pk_mul_f32 v[22:23], v[42:43], v[42:43]
	ds_write2_b64 v37, v[38:39], v[40:41] offset0:192 offset1:194
	v_pk_mul_f32 v[28:29], v[28:29], v[36:37] op_sel_hi:[1,0]
	v_pk_mul_f32 v[38:39], v[26:27], v[26:27]
	v_add_f32_e32 v24, v24, v25
	v_add_f32_e32 v18, v18, v20
	v_pk_mul_f32 v[40:41], v[28:29], v[28:29]
	v_add_f32_e32 v22, v22, v24
	v_add_f32_e32 v18, v19, v18
	v_add_f32_e32 v19, v38, v39
	v_cvt_pk_bf16_f32 v26, v26, v27
	v_cvt_pk_bf16_f32 v27, v28, v29
	v_pk_mul_f32 v[28:29], v[30:31], v[36:37] op_sel_hi:[1,0]
	v_add_f32_e32 v22, v23, v22
	v_add_f32_e32 v19, v40, v19
	v_pk_mul_f32 v[30:31], v[32:33], v[36:37] op_sel_hi:[1,0]
	v_pk_mul_f32 v[32:33], v[28:29], v[28:29]
	v_add_f32_e32 v18, v18, v22
	v_add_f32_e32 v19, v41, v19
	v_pk_mul_f32 v[42:43], v[30:31], v[30:31]
	v_cvt_pk_bf16_f32 v28, v28, v29
	v_cvt_pk_bf16_f32 v29, v30, v31
	v_pk_mul_f32 v[2:3], v[2:3], v[36:37] op_sel_hi:[1,0]
	v_pk_mul_f32 v[4:5], v[4:5], v[36:37] op_sel_hi:[1,0]
	v_add_f32_e32 v18, v19, v18
	v_add_f32_e32 v19, v32, v33
	ds_write2_b64 v37, v[26:27], v[28:29] offset0:196 offset1:198
	v_pk_mul_f32 v[26:27], v[2:3], v[2:3]
	v_pk_mul_f32 v[28:29], v[4:5], v[4:5]
	v_cvt_pk_bf16_f32 v2, v2, v3
	v_cvt_pk_bf16_f32 v3, v4, v5
	v_pk_mul_f32 v[4:5], v[6:7], v[36:37] op_sel_hi:[1,0]
	v_pk_mul_f32 v[6:7], v[8:9], v[36:37] op_sel_hi:[1,0]
	v_add_f32_e32 v19, v42, v19
	v_pk_mul_f32 v[8:9], v[4:5], v[4:5]
	v_cvt_pk_bf16_f32 v4, v4, v5
	v_cvt_pk_bf16_f32 v5, v6, v7
	v_add_f32_e32 v19, v43, v19
	ds_write2_b64 v37, v[2:3], v[4:5] offset0:200 offset1:202
	v_pk_mul_f32 v[2:3], v[10:11], v[36:37] op_sel_hi:[1,0]
	v_pk_mul_f32 v[4:5], v[12:13], v[36:37] op_sel_hi:[1,0]
	v_add_f32_e32 v18, v19, v18
	v_add_f32_e32 v19, v26, v27
	v_pk_mul_f32 v[30:31], v[6:7], v[6:7]
	v_pk_mul_f32 v[6:7], v[2:3], v[2:3]
	v_pk_mul_f32 v[10:11], v[4:5], v[4:5]
	v_cvt_pk_bf16_f32 v13, v4, v5
	v_pk_mul_f32 v[4:5], v[14:15], v[36:37] op_sel_hi:[1,0]
	v_add_f32_e32 v19, v28, v19
	v_add_f32_e32 v8, v8, v9
	v_cvt_pk_bf16_f32 v12, v2, v3
	v_pk_mul_f32 v[14:15], v[16:17], v[36:37] op_sel_hi:[1,0]
	v_pk_mul_f32 v[2:3], v[4:5], v[4:5]
	v_add_f32_e32 v19, v29, v19
	v_add_f32_e32 v8, v30, v8
	v_add_f32_e32 v6, v6, v7
	v_pk_mul_f32 v[16:17], v[14:15], v[14:15]
	v_add_f32_e32 v18, v19, v18
	v_add_f32_e32 v8, v31, v8
	v_add_f32_e32 v6, v10, v6
	v_add_f32_e32 v2, v2, v3
	v_add_f32_e32 v8, v8, v18
	v_add_f32_e32 v6, v11, v6
	v_add_f32_e32 v2, v16, v2
	v_add_f32_e32 v6, v6, v8
	v_add_f32_e32 v2, v17, v2
	v_add_f32_e32 v2, v2, v6
	ds_bpermute_b32 v3, v139, v2
	v_cvt_pk_bf16_f32 v4, v4, v5
	v_cvt_pk_bf16_f32 v5, v14, v15
	ds_write2_b64 v37, v[12:13], v[4:5] offset0:204 offset1:206
	s_and_saveexec_b64 s[2:3], s[36:37]
	s_cbranch_execz .LBB0_707
	s_waitcnt lgkmcnt(1)
	v_add_f32_e32 v2, v2, v3
	s_and_saveexec_b64 s[4:5], s[0:1]
	s_xor_b64 s[0:1], exec, s[4:5]
	s_cbranch_execz .LBB0_705
	s_and_saveexec_b64 s[4:5], vcc
	s_cbranch_execz .LBB0_704
	v_lshl_add_u64 v[4:5], v[34:35], 4, s[26:27]
	v_lshl_add_u64 v[4:5], v[0:1], 2, v[4:5]
	global_store_dword v[4:5], v2, off offset:-24

; DI unsigned pk2(float a, float b) { f2_t v = {a, b}; return __builtin_bit_cast(unsigned, __builtin_convertvector(v, bf2_t)); }
; DI int crow(int i, int h) { return (i & 3) + 8 * (i >> 2) + 4 * h; }
; DI void epi_uq(f32x16 (&acc)[4][2], int m0, int n0, const Params& p, int l, char* lds) {
;     ...
;     for (int mt = 0; mt < 4; ++mt) {
;       const float* rp = p.rope + (size_t)(s0 + mt * 32 + r) * 32;
;       float o1[8], o2[8];
; #pragma unroll
;       for (int i = 0; i < 8; ++i) {
;         const int c1 = crow(i, h);
;         const float x1 = acc[mt][0][i] * rh[mt] * qg[64 + c1], x2 = acc[mt][0][i + 8] * rh[mt] * qg[80 + c1];
;         const float cs = rp[2 * c1], sn = rp[2 * c1 + 1];
;         o1[i] = x1 * cs - x2 * sn; o2[i] = x2 * cs + x1 * sn;
;       }
; #pragma unroll
;       for (int g = 0; g < 2; ++g) {
;         const int c = 8 * g + 4 * h;
;         u32x2 w; w.x = pk2(o1[4 * g], o1[4 * g + 1]); w.y = pk2(o1[4 * g + 2], o1[4 * g + 3]); *(u32x2*)(st + (mt * 32 + r) * 72 + c) = w;
;         u32x2 w2; w2.x = pk2(o2[4 * g], o2[4 * g + 1]); w2.y = pk2(o2[4 * g + 2], o2[4 * g + 3]); *(u32x2*)(st + (mt * 32 + r) * 72 + 16 + c) = w2;
.LBB0_724:
	global_load_dwordx4 v[170:173], v147, s[46:47] offset:256
	global_load_dwordx4 v[174:177], v147, s[46:47] offset:288
	global_load_dwordx4 v[178:181], v147, s[46:47] offset:320
	global_load_dwordx4 v[182:185], v147, s[46:47] offset:352
	v_or_b32_e32 v0, v3, v0
	v_lshlrev_b32_e32 v0, 7, v0
	v_lshl_add_u64 v[30:31], s[30:31], 0, v[0:1]
	v_lshlrev_b32_e32 v0, 5, v2
	v_lshl_add_u64 v[6:7], v[30:31], 0, v[0:1]
	s_mov_b64 s[96:97], 0x1000
	v_lshl_add_u64 v[236:237], v[6:7], 0, s[96:97]
	global_load_dwordx4 v[186:189], v[236:237], off
	global_load_dwordx4 v[190:193], v[236:237], off offset:16
	global_load_dwordx4 v[194:197], v[236:237], off offset:64
	global_load_dwordx4 v[198:201], v[236:237], off offset:80
	v_lshl_add_u64 v[236:237], v[236:237], 0, s[96:97]
	global_load_dwordx4 v[202:205], v[236:237], off
	global_load_dwordx4 v[206:209], v[236:237], off offset:16
	global_load_dwordx4 v[210:213], v[236:237], off offset:64
	global_load_dwordx4 v[218:221], v[236:237], off offset:80
	v_lshl_add_u64 v[236:237], v[236:237], 0, s[96:97]
	global_load_dwordx4 v[222:225], v[236:237], off
	global_load_dwordx4 v[228:231], v[236:237], off offset:16
	global_load_dwordx4 v[232:235], v[236:237], off offset:64
	global_load_dwordx4 v[244:247], v[236:237], off offset:80
	s_waitcnt vmcnt(0)
	v_mov_b64_e32 v[32:33], v[178:179]
	v_pk_mul_f32 v[2:3], v[136:137], v[144:145] op_sel_hi:[1,0]
	v_pk_mul_f32 v[12:13], v[138:139], v[144:145] op_sel_hi:[1,0]
	v_pk_mul_f32 v[76:77], v[130:131], v[144:145] op_sel_hi:[1,0]
	v_pk_mul_f32 v[92:93], v[116:117], v[144:145] op_sel_hi:[1,0]
	s_mov_b64 s[2:3], 0x1000
	v_pk_mul_f32 v[82:83], v[82:83], v[46:47] op_sel_hi:[1,0]
	v_add_u32_e32 v17, 0x1000, v146
	v_pk_mul_f32 v[56:57], v[56:57], v[44:45] op_sel_hi:[1,0]
	s_waitcnt vmcnt(0)
	v_pk_mul_f32 v[10:11], v[2:3], v[32:33]
	global_load_dwordx4 v[2:5], v[6:7], off offset:16
	s_nop 0
	global_load_dwordx4 v[6:9], v[6:7], off
	s_waitcnt vmcnt(0)
	v_mov_b32_e32 v29, v8
	v_mov_b64_e32 v[40:41], v[170:171]
	v_mov_b32_e32 v8, v7
	v_mov_b32_e32 v28, v6
	v_pk_mul_f32 v[6:7], v[10:11], v[8:9]
	s_waitcnt vmcnt(0)
	v_pk_mul_f32 v[12:13], v[12:13], v[40:41]
	s_nop 0
	v_pk_fma_f32 v[48:49], v[12:13], v[28:29], v[6:7] neg_lo:[0,0,1] neg_hi:[0,0,1]
	v_pk_mul_f32 v[6:7], v[12:13], v[8:9]
	v_cvt_pk_bf16_f32 v48, v48, v49
	v_pk_fma_f32 v[62:63], v[10:11], v[28:29], v[6:7]
	v_mov_b64_e32 v[8:9], v[178:179]
	v_mov_b64_e32 v[10:11], v[180:181]
	v_pk_mul_f32 v[6:7], v[132:133], v[144:145] op_sel_hi:[1,0]
	v_pk_mul_f32 v[28:29], v[134:135], v[144:145] op_sel_hi:[1,0]
	s_waitcnt vmcnt(0)
	v_pk_mul_f32 v[6:7], v[6:7], v[10:11]
	v_mov_b64_e32 v[10:11], v[170:171]
	v_mov_b64_e32 v[12:13], v[172:173]
	s_waitcnt vmcnt(0)
	v_pk_mul_f32 v[12:13], v[28:29], v[12:13]
	v_mov_b32_e32 v29, v4
	v_mov_b32_e32 v4, v3
	v_mov_b32_e32 v28, v2
	v_pk_mul_f32 v[2:3], v[6:7], v[4:5]
	s_nop 0
	v_pk_fma_f32 v[64:65], v[12:13], v[28:29], v[2:3] neg_lo:[0,0,1] neg_hi:[0,0,1]
	v_pk_mul_f32 v[2:3], v[12:13], v[4:5]
	v_mov_b64_e32 v[12:13], v[182:183]
	v_pk_fma_f32 v[74:75], v[6:7], v[28:29], v[2:3]
	v_or_b32_e32 v28, 64, v0
	v_mov_b32_e32 v29, v1
	v_lshl_add_u64 v[2:3], v[30:31], 0, v[28:29]
	v_pk_mul_f32 v[4:5], v[118:119], v[144:145] op_sel_hi:[1,0]
	v_cvt_pk_bf16_f32 v49, v64, v65
	s_waitcnt vmcnt(0)
	v_pk_mul_f32 v[6:7], v[4:5], v[12:13]
	global_load_dwordx4 v[58:61], v[2:3], off offset:16
	s_nop 0
	global_load_dwordx4 v[2:5], v[2:3], off
	s_waitcnt vmcnt(0)
	v_mov_b32_e32 v79, v4
	v_mov_b64_e32 v[42:43], v[174:175]
	v_mov_b32_e32 v4, v3
	v_mov_b32_e32 v78, v2
	v_pk_mul_f32 v[2:3], v[6:7], v[4:5]
	s_waitcnt vmcnt(0)
	v_pk_mul_f32 v[76:77], v[76:77], v[42:43]
	s_nop 0
	v_pk_fma_f32 v[80:81], v[76:77], v[78:79], v[2:3] neg_lo:[0,0,1] neg_hi:[0,0,1]
	v_pk_mul_f32 v[2:3], v[76:77], v[4:5]
	s_nop 0
	v_pk_fma_f32 v[76:77], v[6:7], v[78:79], v[2:3]
	v_mov_b64_e32 v[2:3], v[182:183]
	v_mov_b64_e32 v[4:5], v[184:185]
	v_pk_mul_f32 v[6:7], v[114:115], v[144:145] op_sel_hi:[1,0]
	s_waitcnt vmcnt(0)
	v_pk_mul_f32 v[78:79], v[6:7], v[4:5]
	v_mov_b64_e32 v[4:5], v[174:175]
	v_mov_b64_e32 v[6:7], v[176:177]
	s_waitcnt vmcnt(0)
	v_pk_mul_f32 v[6:7], v[92:93], v[6:7]
	v_mov_b32_e32 v93, v60
	v_mov_b32_e32 v60, v59
	v_mov_b32_e32 v92, v58
	v_pk_mul_f32 v[58:59], v[78:79], v[60:61]
	s_nop 0
	v_pk_fma_f32 v[58:59], v[6:7], v[92:93], v[58:59] neg_lo:[0,0,1] neg_hi:[0,0,1]
	v_pk_mul_f32 v[6:7], v[6:7], v[60:61]
	v_cvt_pk_bf16_f32 v60, v62, v63
	v_pk_fma_f32 v[6:7], v[78:79], v[92:93], v[6:7]
	v_cvt_pk_bf16_f32 v62, v80, v81
	v_cvt_pk_bf16_f32 v63, v58, v59
	v_cvt_pk_bf16_f32 v61, v74, v75
	ds_write2_b64 v146, v[48:49], v[62:63] offset1:2
	v_cvt_pk_bf16_f32 v48, v76, v77
	v_cvt_pk_bf16_f32 v49, v6, v7
	v_lshl_add_u64 v[6:7], v[30:31], 0, s[2:3]
	ds_write2_b64 v146, v[60:61], v[48:49] offset0:4 offset1:6
	v_lshl_add_u64 v[48:49], v[6:7], 0, v[0:1]
	v_pk_mul_f32 v[58:59], v[90:91], v[46:47] op_sel_hi:[1,0]
	v_lshl_add_u64 v[6:7], v[6:7], 0, v[28:29]
	v_pk_mul_f32 v[74:75], v[58:59], v[32:33]
	v_mov_b64_e32 v[58:59], v[190:191]
	v_mov_b64_e32 v[60:61], v[192:193]
	v_mov_b64_e32 v[62:63], v[186:187]
	v_mov_b64_e32 v[64:65], v[188:189]
	v_pk_mul_f32 v[48:49], v[110:111], v[46:47] op_sel_hi:[1,0]
	s_mov_b64 s[2:3], 0x2000
	v_pk_mul_f32 v[48:49], v[48:49], v[40:41]
	v_pk_mul_f32 v[32:33], v[56:57], v[32:33]
	s_waitcnt vmcnt(1)
	v_mov_b32_e32 v81, v60
	s_waitcnt vmcnt(0)
; DI unsigned pk2(float a, float b) { f2_t v = {a, b}; return __builtin_bit_cast(unsigned, __builtin_convertvector(v, bf2_t)); }
; DI int crow(int i, int h) { return (i & 3) + 8 * (i >> 2) + 4 * h; }
; DI void epi_uq(f32x16 (&acc)[4][2], int m0, int n0, const Params& p, int l, char* lds) {
;     ...
;     for (int mt = 0; mt < 4; ++mt) {
;       const float* rp = p.rope + (size_t)(s0 + mt * 32 + r) * 32;
;       float o1[8], o2[8];
; #pragma unroll
;       for (int i = 0; i < 8; ++i) {
;         const int c1 = crow(i, h);
;         const float x1 = acc[mt][0][i] * rh[mt] * qg[64 + c1], x2 = acc[mt][0][i + 8] * rh[mt] * qg[80 + c1];
;         const float cs = rp[2 * c1], sn = rp[2 * c1 + 1];
;         o1[i] = x1 * cs - x2 * sn; o2[i] = x2 * cs + x1 * sn;
;       }
; #pragma unroll
;       for (int g = 0; g < 2; ++g) {
;         const int c = 8 * g + 4 * h;
;         u32x2 w; w.x = pk2(o1[4 * g], o1[4 * g + 1]); w.y = pk2(o1[4 * g + 2], o1[4 * g + 3]); *(u32x2*)(st + (mt * 32 + r) * 72 + c) = w;
;         u32x2 w2; w2.x = pk2(o2[4 * g], o2[4 * g + 1]); w2.y = pk2(o2[4 * g + 2], o2[4 * g + 3]); *(u32x2*)(st + (mt * 32 + r) * 72 + 16 + c) = w2;
	v_mov_b32_e32 v77, v64
	v_mov_b32_e32 v64, v63
	v_mov_b32_e32 v76, v62
	v_pk_mul_f32 v[62:63], v[74:75], v[64:65]
	v_mov_b32_e32 v60, v59
	v_pk_fma_f32 v[78:79], v[48:49], v[76:77], v[62:63] neg_lo:[0,0,1] neg_hi:[0,0,1]
	v_pk_mul_f32 v[48:49], v[48:49], v[64:65]
	v_pk_mul_f32 v[62:63], v[88:89], v[46:47] op_sel_hi:[1,0]
	v_pk_fma_f32 v[48:49], v[74:75], v[76:77], v[48:49]
	v_mov_b64_e32 v[74:75], v[180:181]
	v_mov_b64_e32 v[76:77], v[172:173]
	v_pk_mul_f32 v[64:65], v[108:109], v[46:47] op_sel_hi:[1,0]
	v_mov_b32_e32 v80, v58
	v_cvt_pk_bf16_f32 v48, v48, v49
	s_waitcnt vmcnt(1)
	v_pk_mul_f32 v[62:63], v[62:63], v[74:75]
	s_waitcnt vmcnt(0)
	v_pk_mul_f32 v[64:65], v[64:65], v[76:77]
	v_pk_mul_f32 v[58:59], v[62:63], v[60:61]
	s_nop 0
	v_pk_fma_f32 v[88:89], v[64:65], v[80:81], v[58:59] neg_lo:[0,0,1] neg_hi:[0,0,1]
	v_pk_mul_f32 v[58:59], v[64:65], v[60:61]
	s_nop 0
	v_pk_fma_f32 v[80:81], v[62:63], v[80:81], v[58:59]
	v_pk_mul_f32 v[58:59], v[86:87], v[46:47] op_sel_hi:[1,0]
	v_cvt_pk_bf16_f32 v49, v80, v81
	v_pk_mul_f32 v[86:87], v[58:59], v[12:13]
	v_mov_b64_e32 v[58:59], v[198:199]
	v_mov_b64_e32 v[60:61], v[200:201]
	v_mov_b64_e32 v[62:63], v[194:195]
	v_mov_b64_e32 v[64:65], v[196:197]
	v_pk_mul_f32 v[6:7], v[106:107], v[46:47] op_sel_hi:[1,0]
	s_waitcnt vmcnt(0)
	v_mov_b32_e32 v91, v64
	v_mov_b32_e32 v64, v63
	v_pk_mul_f32 v[6:7], v[6:7], v[42:43]
	v_mov_b32_e32 v90, v62
	v_pk_mul_f32 v[62:63], v[86:87], v[64:65]
	s_nop 0
	v_pk_fma_f32 v[62:63], v[6:7], v[90:91], v[62:63] neg_lo:[0,0,1] neg_hi:[0,0,1]
	v_pk_mul_f32 v[6:7], v[6:7], v[64:65]
	v_pk_mul_f32 v[64:65], v[84:85], v[46:47] op_sel_hi:[1,0]
	v_pk_fma_f32 v[6:7], v[86:87], v[90:91], v[6:7]
	v_mov_b64_e32 v[84:85], v[184:185]
	v_mov_b64_e32 v[86:87], v[176:177]
	v_mov_b32_e32 v91, v60
	v_mov_b32_e32 v60, v59
	v_mov_b32_e32 v90, v58
	v_cvt_pk_bf16_f32 v6, v6, v7
	v_cvt_pk_bf16_f32 v62, v62, v63
	s_waitcnt vmcnt(1)
	v_pk_mul_f32 v[64:65], v[64:65], v[84:85]
	s_waitcnt vmcnt(0)
	v_pk_mul_f32 v[82:83], v[82:83], v[86:87]
	v_pk_mul_f32 v[58:59], v[64:65], v[60:61]
	v_pk_mul_f32 v[60:61], v[82:83], v[60:61]
	v_pk_fma_f32 v[58:59], v[82:83], v[90:91], v[58:59] neg_lo:[0,0,1] neg_hi:[0,0,1]
	v_pk_fma_f32 v[60:61], v[64:65], v[90:91], v[60:61]
	v_cvt_pk_bf16_f32 v64, v78, v79
	v_cvt_pk_bf16_f32 v7, v60, v61
	v_cvt_pk_bf16_f32 v65, v88, v89
	v_cvt_pk_bf16_f32 v63, v58, v59
	ds_write2_b64 v17, v[48:49], v[6:7] offset0:68 offset1:70
	v_lshl_add_u64 v[6:7], v[30:31], 0, s[2:3]
	ds_write2_b64 v17, v[64:65], v[62:63] offset0:64 offset1:66
	v_lshl_add_u64 v[48:49], v[6:7], 0, v[0:1]
	v_mov_b64_e32 v[56:57], v[206:207]
	v_mov_b64_e32 v[58:59], v[208:209]
	v_mov_b64_e32 v[60:61], v[202:203]
	v_mov_b64_e32 v[62:63], v[204:205]
	v_pk_mul_f32 v[48:49], v[72:73], v[44:45] op_sel_hi:[1,0]
	v_lshl_add_u64 v[6:7], v[6:7], 0, v[28:29]
	v_pk_mul_f32 v[40:41], v[48:49], v[40:41]
	s_mov_b64 s[2:3], 0x3000
	v_add_u32_e32 v17, 0x2000, v146
	v_lshl_add_u64 v[30:31], v[30:31], 0, s[2:3]
	v_pk_mul_f32 v[24:25], v[24:25], v[16:17] op_sel_hi:[1,0]
	v_lshl_add_u64 v[28:29], v[30:31], 0, v[28:29]
	v_pk_mul_f32 v[18:19], v[18:19], v[16:17] op_sel_hi:[1,0]
	s_movk_i32 s2, 0x1000
	s_waitcnt vmcnt(0)
	v_mov_b32_e32 v49, v62
	v_mov_b32_e32 v62, v61
	v_mov_b32_e32 v48, v60
	v_pk_mul_f32 v[60:61], v[32:33], v[62:63]
	s_nop 0
	v_pk_fma_f32 v[60:61], v[40:41], v[48:49], v[60:61] neg_lo:[0,0,1] neg_hi:[0,0,1]
	v_pk_mul_f32 v[40:41], v[40:41], v[62:63]
	s_nop 0
	v_pk_fma_f32 v[32:33], v[32:33], v[48:49], v[40:41]
	v_pk_mul_f32 v[40:41], v[54:55], v[44:45] op_sel_hi:[1,0]
	v_pk_mul_f32 v[48:49], v[70:71], v[44:45] op_sel_hi:[1,0]
	v_pk_mul_f32 v[40:41], v[40:41], v[74:75]
	v_mov_b32_e32 v55, v58
	v_mov_b32_e32 v58, v57
	v_pk_mul_f32 v[48:49], v[48:49], v[76:77]
	v_mov_b32_e32 v54, v56
	v_pk_mul_f32 v[56:57], v[40:41], v[58:59]
	v_cvt_pk_bf16_f32 v32, v32, v33
	v_pk_fma_f32 v[62:63], v[48:49], v[54:55], v[56:57] neg_lo:[0,0,1] neg_hi:[0,0,1]
	v_pk_mul_f32 v[48:49], v[48:49], v[58:59]
	s_nop 0
	v_pk_fma_f32 v[40:41], v[40:41], v[54:55], v[48:49]
	v_pk_mul_f32 v[48:49], v[52:53], v[44:45] op_sel_hi:[1,0]
	v_mov_b64_e32 v[52:53], v[218:219]
	v_mov_b64_e32 v[54:55], v[220:221]
	v_mov_b64_e32 v[56:57], v[210:211]
	v_mov_b64_e32 v[58:59], v[212:213]
	v_pk_mul_f32 v[6:7], v[68:69], v[44:45] op_sel_hi:[1,0]
	v_pk_mul_f32 v[12:13], v[48:49], v[12:13]
	v_pk_mul_f32 v[6:7], v[6:7], v[42:43]
	v_cvt_pk_bf16_f32 v33, v40, v41
	s_waitcnt vmcnt(0)
	v_mov_b32_e32 v43, v58
	v_mov_b32_e32 v58, v57
	v_mov_b32_e32 v42, v56
	v_pk_mul_f32 v[48:49], v[12:13], v[58:59]
	s_nop 0
	v_pk_fma_f32 v[48:49], v[6:7], v[42:43], v[48:49] neg_lo:[0,0,1] neg_hi:[0,0,1]
	v_pk_mul_f32 v[6:7], v[6:7], v[58:59]
	v_cvt_pk_bf16_f32 v40, v48, v49
	v_pk_fma_f32 v[6:7], v[12:13], v[42:43], v[6:7]
	v_pk_mul_f32 v[12:13], v[50:51], v[44:45] op_sel_hi:[1,0]
	v_pk_mul_f32 v[42:43], v[66:67], v[44:45] op_sel_hi:[1,0]
	v_pk_mul_f32 v[12:13], v[12:13], v[84:85]
	v_mov_b32_e32 v51, v54
	v_mov_b32_e32 v54, v53
	v_pk_mul_f32 v[42:43], v[42:43], v[86:87]
	v_mov_b32_e32 v50, v52
	v_pk_mul_f32 v[52:53], v[12:13], v[54:55]
	v_cvt_pk_bf16_f32 v6, v6, v7
	v_pk_fma_f32 v[52:53], v[42:43], v[50:51], v[52:53] neg_lo:[0,0,1] neg_hi:[0,0,1]
	v_pk_mul_f32 v[42:43], v[42:43], v[54:55]
	v_cvt_pk_bf16_f32 v41, v52, v53
	v_pk_fma_f32 v[12:13], v[12:13], v[50:51], v[42:43]
	v_cvt_pk_bf16_f32 v42, v60, v61
	v_cvt_pk_bf16_f32 v43, v62, v63
	v_cvt_pk_bf16_f32 v7, v12, v13
	ds_write2_b64 v17, v[42:43], v[40:41] offset0:128 offset1:130
	ds_write2_b64 v17, v[32:33], v[6:7] offset0:132 offset1:134
	v_lshl_add_u64 v[12:13], v[30:31], 0, v[0:1]
	v_pk_mul_f32 v[6:7], v[26:27], v[16:17] op_sel_hi:[1,0]
	v_add_u32_e32 v0, 0x3000, v146
	v_pk_mul_f32 v[26:27], v[6:7], v[8:9]
	v_mov_b64_e32 v[6:7], v[228:229]
	v_mov_b64_e32 v[8:9], v[230:231]
	v_mov_b64_e32 v[40:41], v[222:223]
	v_mov_b64_e32 v[42:43], v[224:225]
	v_pk_mul_f32 v[12:13], v[38:39], v[16:17] op_sel_hi:[1,0]
	s_waitcnt vmcnt(0)
; DI unsigned pk2(float a, float b) { f2_t v = {a, b}; return __builtin_bit_cast(unsigned, __builtin_convertvector(v, bf2_t)); }
; DI int crow(int i, int h) { return (i & 3) + 8 * (i >> 2) + 4 * h; }
; DI void epi_uq(f32x16 (&acc)[4][2], int m0, int n0, const Params& p, int l, char* lds) {
;     ...
;     for (int mt = 0; mt < 4; ++mt) {
;       const float* rp = p.rope + (size_t)(s0 + mt * 32 + r) * 32;
;       float o1[8], o2[8];
; #pragma unroll
;       for (int i = 0; i < 8; ++i) {
;         const int c1 = crow(i, h);
;         const float x1 = acc[mt][0][i] * rh[mt] * qg[64 + c1], x2 = acc[mt][0][i + 8] * rh[mt] * qg[80 + c1];
;         const float cs = rp[2 * c1], sn = rp[2 * c1 + 1];
;         o1[i] = x1 * cs - x2 * sn; o2[i] = x2 * cs + x1 * sn;
;       }
; #pragma unroll
;       for (int g = 0; g < 2; ++g) {
;         const int c = 8 * g + 4 * h;
;         u32x2 w; w.x = pk2(o1[4 * g], o1[4 * g + 1]); w.y = pk2(o1[4 * g + 2], o1[4 * g + 3]); *(u32x2*)(st + (mt * 32 + r) * 72 + c) = w;
;         u32x2 w2; w2.x = pk2(o2[4 * g], o2[4 * g + 1]); w2.y = pk2(o2[4 * g + 2], o2[4 * g + 3]); *(u32x2*)(st + (mt * 32 + r) * 72 + 16 + c) = w2;
;       }
;     }
;     const int ch = lane & 3;
; #pragma unroll
;     for (int it = 0; it < 8; ++it) { const int row_l = it * 16 + (lane >> 2); *(u32x4*)(qo + (size_t)row_l * 96 + 64 + ch * 8) = *(const u32x4*)(st + row_l * 72 + ch * 8); }
	v_mov_b32_e32 v33, v42
	v_mov_b32_e32 v42, v41
	v_pk_mul_f32 v[10:11], v[12:13], v[10:11]
	v_mov_b32_e32 v32, v40
	v_pk_mul_f32 v[12:13], v[26:27], v[42:43]
	s_nop 0
	v_pk_fma_f32 v[12:13], v[10:11], v[32:33], v[12:13] neg_lo:[0,0,1] neg_hi:[0,0,1]
	v_pk_mul_f32 v[10:11], v[10:11], v[42:43]
	v_cvt_pk_bf16_f32 v12, v12, v13
	v_pk_fma_f32 v[10:11], v[26:27], v[32:33], v[10:11]
	v_mov_b64_e32 v[26:27], v[180:181]
	v_mov_b64_e32 v[32:33], v[172:173]
	v_cvt_pk_bf16_f32 v10, v10, v11
	s_waitcnt vmcnt(1)
	v_pk_mul_f32 v[24:25], v[24:25], v[26:27]
	v_pk_mul_f32 v[26:27], v[36:37], v[16:17] op_sel_hi:[1,0]
	v_mov_b32_e32 v37, v8
	v_mov_b32_e32 v8, v7
	s_waitcnt vmcnt(0)
	v_pk_mul_f32 v[32:33], v[26:27], v[32:33]
	v_mov_b32_e32 v36, v6
	v_pk_mul_f32 v[6:7], v[24:25], v[8:9]
	s_nop 0
	v_pk_fma_f32 v[26:27], v[32:33], v[36:37], v[6:7] neg_lo:[0,0,1] neg_hi:[0,0,1]
	v_pk_mul_f32 v[6:7], v[32:33], v[8:9]
	v_cvt_pk_bf16_f32 v13, v26, v27
	v_pk_fma_f32 v[24:25], v[24:25], v[36:37], v[6:7]
	v_pk_mul_f32 v[6:7], v[20:21], v[16:17] op_sel_hi:[1,0]
	v_pk_mul_f32 v[20:21], v[34:35], v[16:17] op_sel_hi:[1,0]
	v_pk_mul_f32 v[2:3], v[6:7], v[2:3]
	v_mov_b64_e32 v[6:7], v[244:245]
	v_mov_b64_e32 v[8:9], v[246:247]
	s_nop 0
	v_mov_b64_e32 v[28:29], v[232:233]
	v_mov_b64_e32 v[30:31], v[234:235]
	v_pk_mul_f32 v[20:21], v[20:21], v[4:5]
	v_pk_mul_f32 v[16:17], v[22:23], v[16:17] op_sel_hi:[1,0]
	v_cvt_pk_bf16_f32 v11, v24, v25
	s_waitcnt vmcnt(0)
	v_mov_b32_e32 v33, v30
	v_mov_b32_e32 v30, v29
	v_mov_b32_e32 v32, v28
	v_pk_mul_f32 v[4:5], v[2:3], v[30:31]
	s_nop 0
	v_pk_fma_f32 v[4:5], v[20:21], v[32:33], v[4:5] neg_lo:[0,0,1] neg_hi:[0,0,1]
	v_pk_mul_f32 v[20:21], v[20:21], v[30:31]
	v_cvt_pk_bf16_f32 v4, v4, v5
	v_pk_fma_f32 v[2:3], v[2:3], v[32:33], v[20:21]
	v_mov_b64_e32 v[20:21], v[184:185]
	v_cvt_pk_bf16_f32 v2, v2, v3
	s_waitcnt vmcnt(0)
	v_pk_mul_f32 v[18:19], v[18:19], v[20:21]
	v_mov_b64_e32 v[20:21], v[176:177]
	s_waitcnt vmcnt(0)
	v_pk_mul_f32 v[16:17], v[16:17], v[20:21]
	v_mov_b32_e32 v21, v8
	v_mov_b32_e32 v8, v7
	v_mov_b32_e32 v20, v6
	v_pk_mul_f32 v[6:7], v[18:19], v[8:9]
	v_pk_mul_f32 v[8:9], v[16:17], v[8:9]
	v_pk_fma_f32 v[6:7], v[16:17], v[20:21], v[6:7] neg_lo:[0,0,1] neg_hi:[0,0,1]
	v_pk_fma_f32 v[8:9], v[18:19], v[20:21], v[8:9]
	v_cvt_pk_bf16_f32 v5, v6, v7
	v_cvt_pk_bf16_f32 v3, v8, v9
	ds_write2_b64 v0, v[12:13], v[4:5] offset0:192 offset1:194
	ds_write2_b64 v0, v[10:11], v[2:3] offset0:196 offset1:198
	v_lshrrev_b32_e32 v0, 2, v45
	v_and_b32_e32 v6, 48, v145
	v_mul_u32_u24_e32 v2, 0x90, v0
	v_add3_u32 v12, v47, v6, v2
	ds_read_b128 v[2:5], v12
	v_mul_u32_u24_e32 v0, 0x60, v0
	v_lshlrev_b32_e32 v0, 1, v0
	v_lshl_add_u64 v[8:9], v[14:15], 0, v[0:1]
	v_mov_b32_e32 v7, v1
	v_lshl_add_u64 v[8:9], v[8:9], 0, v[6:7]
	s_waitcnt lgkmcnt(0)
	global_store_dwordx4 v[8:9], v[2:5], off offset:128
	ds_read_b128 v[2:5], v12 offset:2304
	v_add_co_u32_e32 v10, vcc, s2, v8
	s_movk_i32 s2, 0x2000
	s_nop 0
	v_addc_co_u32_e32 v11, vcc, 0, v9, vcc
	s_waitcnt lgkmcnt(0)
	global_store_dwordx4 v[8:9], v[2:5], off offset:3200
	ds_read_b128 v[2:5], v12 offset:4608
	v_add_co_u32_e32 v8, vcc, s2, v8
	s_waitcnt lgkmcnt(0)
	global_store_dwordx4 v[10:11], v[2:5], off offset:2176
	ds_read_b128 v[2:5], v12 offset:6912
	v_addc_co_u32_e32 v9, vcc, 0, v9, vcc
	s_waitcnt lgkmcnt(0)
	global_store_dwordx4 v[8:9], v[2:5], off offset:1152
	ds_read_b128 v[2:5], v12 offset:9216
	v_or_b32_e32 v8, 0x3000, v0
	v_mov_b32_e32 v9, v1
	v_lshl_add_u64 v[8:9], v[14:15], 0, v[8:9]
	v_lshl_add_u64 v[8:9], v[8:9], 0, v[6:7]
	s_waitcnt lgkmcnt(0)
	global_store_dwordx4 v[8:9], v[2:5], off offset:128
	ds_read_b128 v[2:5], v12 offset:11520
	v_add_u32_e32 v8, 0x3c00, v0
	v_mov_b32_e32 v9, v1
	v_lshl_add_u64 v[8:9], v[14:15], 0, v[8:9]
	v_lshl_add_u64 v[8:9], v[8:9], 0, v[6:7]
	s_waitcnt lgkmcnt(0)
	global_store_dwordx4 v[8:9], v[2:5], off offset:128
	ds_read_b128 v[2:5], v12 offset:13824
	v_add_u32_e32 v8, 0x4800, v0
	v_mov_b32_e32 v9, v1
	v_lshl_add_u64 v[8:9], v[14:15], 0, v[8:9]
	v_lshl_add_u64 v[8:9], v[8:9], 0, v[6:7]
	s_waitcnt lgkmcnt(0)
	global_store_dwordx4 v[8:9], v[2:5], off offset:128
	ds_read_b128 v[2:5], v12 offset:16128
	v_add_u32_e32 v0, 0x5400, v0
	v_lshl_add_u64 v[8:9], v[14:15], 0, v[0:1]
	v_lshl_add_u64 v[6:7], v[8:9], 0, v[6:7]
	s_waitcnt lgkmcnt(0)
	global_store_dwordx4 v[6:7], v[2:5], off offset:128
	s_andn2_saveexec_b64 s[0:1], s[0:1]
	s_cbranch_execz .LBB0_709
; DI unsigned pk2(float a, float b) { f2_t v = {a, b}; return __builtin_bit_cast(unsigned, __builtin_convertvector(v, bf2_t)); }
; DI void epi_uq(f32x16 (&acc)[4][2], int m0, int n0, const Params& p, int l, char* lds) {
;     ...
;   if (wch == 0) {
; #pragma unroll
;     for (int mt = 0; mt < 4; ++mt)
; #pragma unroll
;       for (int nt = 0; nt < 2; ++nt)
; #pragma unroll
;         for (int g = 0; g < 4; ++g) {
;           const int c = nt * 32 + 8 * g + 4 * h;
;           const f32x4 gg = *(const f32x4*)(qg + c);
;           u32x2 w; w.x = pk2(acc[mt][nt][4 * g] * rh[mt] * gg.x, acc[mt][nt][4 * g + 1] * rh[mt] * gg.y); w.y = pk2(acc[mt][nt][4 * g + 2] * rh[mt] * gg.z, acc[mt][nt][4 * g + 3] * rh[mt] * gg.w);
;           *(u32x2*)(st + (mt * 32 + r) * 72 + c) = w;
;         }
.LBB0_725:
	global_load_dwordx4 v[170:173], v147, s[46:47]
	global_load_dwordx4 v[174:177], v147, s[46:47] offset:32
	global_load_dwordx4 v[178:181], v147, s[46:47] offset:64
	global_load_dwordx4 v[182:185], v147, s[46:47] offset:96
	global_load_dwordx4 v[186:189], v147, s[46:47] offset:128
	global_load_dwordx4 v[190:193], v147, s[46:47] offset:160
	global_load_dwordx4 v[194:197], v147, s[46:47] offset:192
	global_load_dwordx4 v[198:201], v147, s[46:47] offset:224
	s_waitcnt vmcnt(0)
	v_mov_b64_e32 v[2:3], v[170:171]
	v_mov_b64_e32 v[4:5], v[172:173]
	v_mov_b64_e32 v[148:149], v[174:175]
	v_mov_b64_e32 v[150:151], v[176:177]
	v_pk_mul_f32 v[12:13], v[138:139], v[144:145] op_sel_hi:[1,0]
	v_pk_mul_f32 v[134:135], v[134:135], v[144:145] op_sel_hi:[1,0]
	v_pk_mul_f32 v[130:131], v[130:131], v[144:145] op_sel_hi:[1,0]
	v_pk_mul_f32 v[116:117], v[116:117], v[144:145] op_sel_hi:[1,0]
	v_pk_mul_f32 v[114:115], v[114:115], v[144:145] op_sel_hi:[1,0]
	v_pk_mul_f32 v[98:99], v[98:99], v[144:145] op_sel_hi:[1,0]
	v_pk_mul_f32 v[100:101], v[100:101], v[144:145] op_sel_hi:[1,0]
	v_pk_mul_f32 v[82:83], v[82:83], v[46:47] op_sel_hi:[1,0]
	v_add_u32_e32 v0, 0x1000, v146
	v_pk_mul_f32 v[84:85], v[84:85], v[46:47] op_sel_hi:[1,0]
	v_pk_mul_f32 v[76:77], v[76:77], v[46:47] op_sel_hi:[1,0]
	v_pk_mul_f32 v[74:75], v[74:75], v[46:47] op_sel_hi:[1,0]
	v_pk_mul_f32 v[70:71], v[70:71], v[44:45] op_sel_hi:[1,0]
	v_pk_mul_f32 v[68:69], v[68:69], v[44:45] op_sel_hi:[1,0]
	v_pk_mul_f32 v[66:67], v[66:67], v[44:45] op_sel_hi:[1,0]
	v_pk_mul_f32 v[52:53], v[52:53], v[44:45] op_sel_hi:[1,0]
	v_pk_mul_f32 v[50:51], v[50:51], v[44:45] op_sel_hi:[1,0]
	v_pk_mul_f32 v[48:49], v[48:49], v[44:45] op_sel_hi:[1,0]
	v_pk_mul_f32 v[34:35], v[34:35], v[16:17] op_sel_hi:[1,0]
	v_pk_mul_f32 v[22:23], v[22:23], v[16:17] op_sel_hi:[1,0]
	v_pk_mul_f32 v[20:21], v[20:21], v[16:17] op_sel_hi:[1,0]
	v_pk_mul_f32 v[18:19], v[18:19], v[16:17] op_sel_hi:[1,0]
	v_pk_mul_f32 v[10:11], v[10:11], v[16:17] op_sel_hi:[1,0]
	v_pk_mul_f32 v[6:7], v[6:7], v[16:17] op_sel_hi:[1,0]
	s_mov_b64 s[2:3], 0x600
	s_waitcnt vmcnt(1)
	v_pk_mul_f32 v[12:13], v[12:13], v[2:3]
	v_pk_mul_f32 v[134:135], v[134:135], v[4:5]
	s_waitcnt vmcnt(0)
	v_pk_mul_f32 v[130:131], v[130:131], v[148:149]
	v_pk_mul_f32 v[116:117], v[116:117], v[150:151]
	v_mov_b64_e32 v[148:149], v[178:179]
	v_mov_b64_e32 v[150:151], v[180:181]
	v_cvt_pk_bf16_f32 v12, v12, v13
	v_cvt_pk_bf16_f32 v13, v134, v135
	v_cvt_pk_bf16_f32 v130, v130, v131
	v_cvt_pk_bf16_f32 v131, v116, v117
	ds_write2_b64 v146, v[12:13], v[130:131] offset1:2
	v_pk_mul_f32 v[116:117], v[132:133], v[144:145] op_sel_hi:[1,0]
	v_mov_b64_e32 v[130:131], v[182:183]
	v_mov_b64_e32 v[132:133], v[184:185]
	v_pk_mul_f32 v[12:13], v[136:137], v[144:145] op_sel_hi:[1,0]
	s_waitcnt vmcnt(1)
	v_pk_mul_f32 v[116:117], v[116:117], v[150:151]
	v_pk_mul_f32 v[12:13], v[12:13], v[148:149]
	s_waitcnt vmcnt(0)
	v_pk_mul_f32 v[114:115], v[114:115], v[132:133]
	v_cvt_pk_bf16_f32 v12, v12, v13
	v_cvt_pk_bf16_f32 v13, v116, v117
	v_pk_mul_f32 v[116:117], v[118:119], v[144:145] op_sel_hi:[1,0]
	v_pk_mul_f32 v[118:119], v[120:121], v[144:145] op_sel_hi:[1,0]
	v_pk_mul_f32 v[116:117], v[116:117], v[130:131]
	s_nop 0
	v_cvt_pk_bf16_f32 v116, v116, v117
	v_cvt_pk_bf16_f32 v117, v114, v115
	ds_write2_b64 v146, v[12:13], v[116:117] offset0:4 offset1:6
	v_mov_b64_e32 v[114:115], v[186:187]
	v_mov_b64_e32 v[116:117], v[188:189]
	v_pk_mul_f32 v[12:13], v[124:125], v[144:145] op_sel_hi:[1,0]
	s_waitcnt vmcnt(0)
	v_pk_mul_f32 v[12:13], v[12:13], v[114:115]
	v_pk_mul_f32 v[114:115], v[126:127], v[144:145] op_sel_hi:[1,0]
	v_cvt_pk_bf16_f32 v12, v12, v13
	v_pk_mul_f32 v[114:115], v[114:115], v[116:117]
	s_nop 0
	v_cvt_pk_bf16_f32 v13, v114, v115
	v_mov_b64_e32 v[114:115], v[190:191]
	v_mov_b64_e32 v[116:117], v[192:193]
	s_waitcnt vmcnt(0)
	v_pk_mul_f32 v[114:115], v[118:119], v[114:115]
	v_pk_mul_f32 v[118:119], v[122:123], v[144:145] op_sel_hi:[1,0]
	v_cvt_pk_bf16_f32 v114, v114, v115
	v_pk_mul_f32 v[116:117], v[118:119], v[116:117]
	s_nop 0
	v_cvt_pk_bf16_f32 v115, v116, v117
	ds_write2_b64 v146, v[12:13], v[114:115] offset0:8 offset1:10
	v_mov_b64_e32 v[114:115], v[194:195]
	v_mov_b64_e32 v[116:117], v[196:197]
	v_pk_mul_f32 v[12:13], v[102:103], v[144:145] op_sel_hi:[1,0]
	v_pk_mul_f32 v[102:103], v[104:105], v[144:145] op_sel_hi:[1,0]
	s_waitcnt vmcnt(0)
	v_pk_mul_f32 v[12:13], v[12:13], v[114:115]
	v_pk_mul_f32 v[102:103], v[102:103], v[116:117]
	v_cvt_pk_bf16_f32 v12, v12, v13
	v_cvt_pk_bf16_f32 v13, v102, v103
	v_mov_b64_e32 v[102:103], v[198:199]
	v_mov_b64_e32 v[104:105], v[200:201]
	s_waitcnt vmcnt(0)
	v_pk_mul_f32 v[98:99], v[98:99], v[102:103]
	v_pk_mul_f32 v[100:101], v[100:101], v[104:105]
	v_cvt_pk_bf16_f32 v98, v98, v99
	v_cvt_pk_bf16_f32 v99, v100, v101
	ds_write2_b64 v146, v[12:13], v[98:99] offset0:12 offset1:14
	v_pk_mul_f32 v[12:13], v[110:111], v[46:47] op_sel_hi:[1,0]
	v_pk_mul_f32 v[98:99], v[106:107], v[46:47] op_sel_hi:[1,0]
	v_pk_mul_f32 v[2:3], v[12:13], v[2:3]
	s_nop 0
	v_cvt_pk_bf16_f32 v12, v2, v3
	v_pk_mul_f32 v[2:3], v[108:109], v[46:47] op_sel_hi:[1,0]
	s_nop 0
	v_pk_mul_f32 v[2:3], v[2:3], v[4:5]
	s_nop 0
	v_cvt_pk_bf16_f32 v13, v2, v3
	v_mov_b64_e32 v[2:3], v[174:175]
	v_mov_b64_e32 v[4:5], v[176:177]
	s_waitcnt vmcnt(0)
	v_pk_mul_f32 v[98:99], v[98:99], v[2:3]
	v_pk_mul_f32 v[82:83], v[82:83], v[4:5]
	v_cvt_pk_bf16_f32 v98, v98, v99
	v_cvt_pk_bf16_f32 v99, v82, v83
	ds_write2_b64 v0, v[12:13], v[98:99] offset0:64 offset1:66
	v_mov_b64_e32 v[98:99], v[178:179]
	v_mov_b64_e32 v[100:101], v[180:181]
	v_pk_mul_f32 v[12:13], v[90:91], v[46:47] op_sel_hi:[1,0]
	v_pk_mul_f32 v[82:83], v[88:89], v[46:47] op_sel_hi:[1,0]
	v_mov_b64_e32 v[88:89], v[182:183]
	v_mov_b64_e32 v[90:91], v[184:185]
	v_pk_mul_f32 v[2:3], v[68:69], v[2:3]
	v_pk_mul_f32 v[4:5], v[66:67], v[4:5]
	v_cvt_pk_bf16_f32 v2, v2, v3
	v_cvt_pk_bf16_f32 v3, v4, v5
	s_waitcnt vmcnt(1)
; DI unsigned pk2(float a, float b) { f2_t v = {a, b}; return __builtin_bit_cast(unsigned, __builtin_convertvector(v, bf2_t)); }
; DI void epi_uq(f32x16 (&acc)[4][2], int m0, int n0, const Params& p, int l, char* lds) {
;     ...
; #pragma unroll
;     for (int mt = 0; mt < 4; ++mt)
; #pragma unroll
;       for (int nt = 0; nt < 2; ++nt)
; #pragma unroll
;         for (int g = 0; g < 4; ++g) {
;           const int c = nt * 32 + 8 * g + 4 * h;
;           const f32x4 gg = *(const f32x4*)(qg + c);
;           u32x2 w; w.x = pk2(acc[mt][nt][4 * g] * rh[mt] * gg.x, acc[mt][nt][4 * g + 1] * rh[mt] * gg.y); w.y = pk2(acc[mt][nt][4 * g + 2] * rh[mt] * gg.z, acc[mt][nt][4 * g + 3] * rh[mt] * gg.w);
;           *(u32x2*)(st + (mt * 32 + r) * 72 + c) = w;
;         }
	v_pk_mul_f32 v[12:13], v[12:13], v[98:99]
	v_pk_mul_f32 v[82:83], v[82:83], v[100:101]
	v_cvt_pk_bf16_f32 v12, v12, v13
	v_cvt_pk_bf16_f32 v13, v82, v83
	v_pk_mul_f32 v[82:83], v[86:87], v[46:47] op_sel_hi:[1,0]
	s_waitcnt vmcnt(0)
	v_pk_mul_f32 v[84:85], v[84:85], v[90:91]
	v_pk_mul_f32 v[82:83], v[82:83], v[88:89]
	v_pk_mul_f32 v[86:87], v[112:113], v[46:47] op_sel_hi:[1,0]
	v_cvt_pk_bf16_f32 v82, v82, v83
	v_cvt_pk_bf16_f32 v83, v84, v85
	ds_write2_b64 v0, v[12:13], v[82:83] offset0:68 offset1:70
	v_mov_b64_e32 v[82:83], v[186:187]
	v_mov_b64_e32 v[84:85], v[188:189]
	v_pk_mul_f32 v[12:13], v[140:141], v[46:47] op_sel_hi:[1,0]
	s_waitcnt vmcnt(0)
	v_pk_mul_f32 v[12:13], v[12:13], v[82:83]
	v_pk_mul_f32 v[82:83], v[128:129], v[46:47] op_sel_hi:[1,0]
	v_cvt_pk_bf16_f32 v12, v12, v13
	v_pk_mul_f32 v[82:83], v[82:83], v[84:85]
	s_nop 0
	v_cvt_pk_bf16_f32 v13, v82, v83
	v_mov_b64_e32 v[82:83], v[190:191]
	v_mov_b64_e32 v[84:85], v[192:193]
	s_waitcnt vmcnt(0)
	v_pk_mul_f32 v[82:83], v[86:87], v[82:83]
	v_pk_mul_f32 v[86:87], v[96:97], v[46:47] op_sel_hi:[1,0]
	v_cvt_pk_bf16_f32 v82, v82, v83
	v_pk_mul_f32 v[84:85], v[86:87], v[84:85]
	s_nop 0
	v_cvt_pk_bf16_f32 v83, v84, v85
	ds_write2_b64 v0, v[12:13], v[82:83] offset0:72 offset1:74
	v_mov_b64_e32 v[82:83], v[194:195]
	v_mov_b64_e32 v[84:85], v[196:197]
	v_pk_mul_f32 v[12:13], v[94:95], v[46:47] op_sel_hi:[1,0]
	s_waitcnt vmcnt(0)
	v_pk_mul_f32 v[12:13], v[12:13], v[82:83]
	v_pk_mul_f32 v[82:83], v[92:93], v[46:47] op_sel_hi:[1,0]
	v_cvt_pk_bf16_f32 v12, v12, v13
	v_pk_mul_f32 v[82:83], v[82:83], v[84:85]
	s_nop 0
	v_cvt_pk_bf16_f32 v13, v82, v83
	v_mov_b64_e32 v[82:83], v[198:199]
	v_mov_b64_e32 v[84:85], v[200:201]
	s_waitcnt vmcnt(0)
	v_pk_mul_f32 v[76:77], v[76:77], v[82:83]
	v_pk_mul_f32 v[74:75], v[74:75], v[84:85]
	v_cvt_pk_bf16_f32 v76, v76, v77
	v_cvt_pk_bf16_f32 v77, v74, v75
	ds_write2_b64 v0, v[12:13], v[76:77] offset0:76 offset1:78
	v_mov_b64_e32 v[74:75], v[170:171]
	v_mov_b64_e32 v[76:77], v[172:173]
	v_pk_mul_f32 v[12:13], v[72:73], v[44:45] op_sel_hi:[1,0]
	v_add_u32_e32 v0, 0x2000, v146
	s_waitcnt vmcnt(0)
	v_pk_mul_f32 v[12:13], v[12:13], v[74:75]
	v_pk_mul_f32 v[70:71], v[70:71], v[76:77]
	v_cvt_pk_bf16_f32 v12, v12, v13
	v_cvt_pk_bf16_f32 v13, v70, v71
	ds_write2_b64 v0, v[12:13], v[2:3] offset0:128 offset1:130
	v_mov_b64_e32 v[2:3], v[178:179]
	v_mov_b64_e32 v[4:5], v[180:181]
	v_pk_mul_f32 v[12:13], v[56:57], v[44:45] op_sel_hi:[1,0]
	s_waitcnt vmcnt(0)
	v_pk_mul_f32 v[2:3], v[12:13], v[2:3]
	s_nop 0
	v_cvt_pk_bf16_f32 v12, v2, v3
	v_pk_mul_f32 v[2:3], v[54:55], v[44:45] op_sel_hi:[1,0]
	s_nop 0
	v_pk_mul_f32 v[2:3], v[2:3], v[4:5]
	s_nop 0
	v_cvt_pk_bf16_f32 v13, v2, v3
	v_mov_b64_e32 v[2:3], v[182:183]
	v_mov_b64_e32 v[4:5], v[184:185]
	s_waitcnt vmcnt(0)
	v_pk_mul_f32 v[2:3], v[52:53], v[2:3]
	v_pk_mul_f32 v[4:5], v[50:51], v[4:5]
	v_cvt_pk_bf16_f32 v2, v2, v3
	v_cvt_pk_bf16_f32 v3, v4, v5
	ds_write2_b64 v0, v[12:13], v[2:3] offset0:132 offset1:134
	v_mov_b64_e32 v[2:3], v[186:187]
	v_mov_b64_e32 v[4:5], v[188:189]
	v_pk_mul_f32 v[12:13], v[142:143], v[44:45] op_sel_hi:[1,0]
	v_pk_mul_f32 v[50:51], v[78:79], v[44:45] op_sel_hi:[1,0]
	s_waitcnt vmcnt(0)
	v_pk_mul_f32 v[2:3], v[12:13], v[2:3]
	s_nop 0
	v_cvt_pk_bf16_f32 v12, v2, v3
	v_pk_mul_f32 v[2:3], v[80:81], v[44:45] op_sel_hi:[1,0]
	s_nop 0
	v_pk_mul_f32 v[2:3], v[2:3], v[4:5]
	s_nop 0
	v_cvt_pk_bf16_f32 v13, v2, v3
	v_mov_b64_e32 v[2:3], v[190:191]
	v_mov_b64_e32 v[4:5], v[192:193]
	s_waitcnt vmcnt(0)
	v_pk_mul_f32 v[2:3], v[50:51], v[2:3]
	v_pk_mul_f32 v[50:51], v[64:65], v[44:45] op_sel_hi:[1,0]
	v_cvt_pk_bf16_f32 v2, v2, v3
	v_pk_mul_f32 v[4:5], v[50:51], v[4:5]
	v_pk_mul_f32 v[50:51], v[58:59], v[44:45] op_sel_hi:[1,0]
	v_cvt_pk_bf16_f32 v3, v4, v5
	ds_write2_b64 v0, v[12:13], v[2:3] offset0:136 offset1:138
	v_mov_b64_e32 v[2:3], v[194:195]
	v_mov_b64_e32 v[4:5], v[196:197]
	v_pk_mul_f32 v[12:13], v[62:63], v[44:45] op_sel_hi:[1,0]
	s_waitcnt vmcnt(0)
	v_pk_mul_f32 v[2:3], v[12:13], v[2:3]
	s_nop 0
	v_cvt_pk_bf16_f32 v12, v2, v3
	v_pk_mul_f32 v[2:3], v[60:61], v[44:45] op_sel_hi:[1,0]
	s_nop 0
	v_pk_mul_f32 v[2:3], v[2:3], v[4:5]
	s_nop 0
	v_cvt_pk_bf16_f32 v13, v2, v3
	v_mov_b64_e32 v[2:3], v[198:199]
	v_mov_b64_e32 v[4:5], v[200:201]
	s_waitcnt vmcnt(0)
	v_pk_mul_f32 v[2:3], v[50:51], v[2:3]
	v_pk_mul_f32 v[4:5], v[48:49], v[4:5]
	v_cvt_pk_bf16_f32 v2, v2, v3
	v_cvt_pk_bf16_f32 v3, v4, v5
	ds_write2_b64 v0, v[12:13], v[2:3] offset0:140 offset1:142
	v_mov_b64_e32 v[2:3], v[170:171]
	v_mov_b64_e32 v[4:5], v[172:173]
	v_pk_mul_f32 v[12:13], v[38:39], v[16:17] op_sel_hi:[1,0]
	v_add_u32_e32 v0, 0x3000, v146
	s_waitcnt vmcnt(0)
	v_pk_mul_f32 v[2:3], v[12:13], v[2:3]
	s_nop 0
	v_cvt_pk_bf16_f32 v12, v2, v3
	v_pk_mul_f32 v[2:3], v[36:37], v[16:17] op_sel_hi:[1,0]
	s_nop 0
	v_pk_mul_f32 v[2:3], v[2:3], v[4:5]
	s_nop 0
	v_cvt_pk_bf16_f32 v13, v2, v3
	v_mov_b64_e32 v[2:3], v[174:175]
	v_mov_b64_e32 v[4:5], v[176:177]
	s_waitcnt vmcnt(0)
	v_pk_mul_f32 v[2:3], v[34:35], v[2:3]
	v_pk_mul_f32 v[4:5], v[22:23], v[4:5]
	v_cvt_pk_bf16_f32 v2, v2, v3
	v_cvt_pk_bf16_f32 v3, v4, v5
	ds_write2_b64 v0, v[12:13], v[2:3] offset0:192 offset1:194
	v_mov_b64_e32 v[2:3], v[178:179]
	v_mov_b64_e32 v[4:5], v[180:181]
	v_pk_mul_f32 v[12:13], v[26:27], v[16:17] op_sel_hi:[1,0]
	s_waitcnt vmcnt(0)
; DI unsigned pk2(float a, float b) { f2_t v = {a, b}; return __builtin_bit_cast(unsigned, __builtin_convertvector(v, bf2_t)); }
; DI void epi_uq(f32x16 (&acc)[4][2], int m0, int n0, const Params& p, int l, char* lds) {
;     ...
; #pragma unroll
;     for (int mt = 0; mt < 4; ++mt)
; #pragma unroll
;       for (int nt = 0; nt < 2; ++nt)
; #pragma unroll
;         for (int g = 0; g < 4; ++g) {
;           const int c = nt * 32 + 8 * g + 4 * h;
;           const f32x4 gg = *(const f32x4*)(qg + c);
;           u32x2 w; w.x = pk2(acc[mt][nt][4 * g] * rh[mt] * gg.x, acc[mt][nt][4 * g + 1] * rh[mt] * gg.y); w.y = pk2(acc[mt][nt][4 * g + 2] * rh[mt] * gg.z, acc[mt][nt][4 * g + 3] * rh[mt] * gg.w);
;           *(u32x2*)(st + (mt * 32 + r) * 72 + c) = w;
;         }
;     const int ch = lane & 7;
; #pragma unroll
;     for (int it = 0; it < 16; ++it) { const int row_l = it * 8 + (lane >> 3); *(u32x4*)(qo + (size_t)row_l * 96 + ch * 8) = *(const u32x4*)(st + row_l * 72 + ch * 8); }
	v_pk_mul_f32 v[2:3], v[12:13], v[2:3]
	s_nop 0
	v_cvt_pk_bf16_f32 v12, v2, v3
	v_pk_mul_f32 v[2:3], v[24:25], v[16:17] op_sel_hi:[1,0]
	s_nop 0
	v_pk_mul_f32 v[2:3], v[2:3], v[4:5]
	s_nop 0
	v_cvt_pk_bf16_f32 v13, v2, v3
	v_mov_b64_e32 v[2:3], v[182:183]
	v_mov_b64_e32 v[4:5], v[184:185]
	s_waitcnt vmcnt(0)
	v_pk_mul_f32 v[2:3], v[20:21], v[2:3]
	v_pk_mul_f32 v[4:5], v[18:19], v[4:5]
	v_cvt_pk_bf16_f32 v2, v2, v3
	v_cvt_pk_bf16_f32 v3, v4, v5
	ds_write2_b64 v0, v[12:13], v[2:3] offset0:196 offset1:198
	v_mov_b64_e32 v[2:3], v[186:187]
	v_mov_b64_e32 v[4:5], v[188:189]
	v_pk_mul_f32 v[12:13], v[42:43], v[16:17] op_sel_hi:[1,0]
	v_pk_mul_f32 v[18:19], v[32:33], v[16:17] op_sel_hi:[1,0]
	s_waitcnt vmcnt(0)
	v_pk_mul_f32 v[2:3], v[12:13], v[2:3]
	s_nop 0
	v_cvt_pk_bf16_f32 v12, v2, v3
	v_pk_mul_f32 v[2:3], v[40:41], v[16:17] op_sel_hi:[1,0]
	s_nop 0
	v_pk_mul_f32 v[2:3], v[2:3], v[4:5]
	s_nop 0
	v_cvt_pk_bf16_f32 v13, v2, v3
	v_mov_b64_e32 v[2:3], v[190:191]
	v_mov_b64_e32 v[4:5], v[192:193]
	s_waitcnt vmcnt(0)
	v_pk_mul_f32 v[2:3], v[18:19], v[2:3]
	v_pk_mul_f32 v[18:19], v[30:31], v[16:17] op_sel_hi:[1,0]
	v_cvt_pk_bf16_f32 v2, v2, v3
	v_pk_mul_f32 v[4:5], v[18:19], v[4:5]
	s_nop 0
	v_cvt_pk_bf16_f32 v3, v4, v5
	ds_write2_b64 v0, v[12:13], v[2:3] offset0:200 offset1:202
	v_mov_b64_e32 v[2:3], v[194:195]
	v_mov_b64_e32 v[4:5], v[196:197]
	v_pk_mul_f32 v[12:13], v[28:29], v[16:17] op_sel_hi:[1,0]
	s_waitcnt vmcnt(0)
	v_pk_mul_f32 v[4:5], v[10:11], v[4:5]
	v_pk_mul_f32 v[2:3], v[12:13], v[2:3]
	v_mov_b64_e32 v[10:11], v[198:199]
	v_mov_b64_e32 v[12:13], v[200:201]
	v_cvt_pk_bf16_f32 v2, v2, v3
	v_cvt_pk_bf16_f32 v3, v4, v5
	v_pk_mul_f32 v[4:5], v[8:9], v[16:17] op_sel_hi:[1,0]
	v_lshrrev_b32_e32 v8, 3, v45
	s_waitcnt vmcnt(0)
	v_pk_mul_f32 v[4:5], v[4:5], v[10:11]
	v_pk_mul_f32 v[6:7], v[6:7], v[12:13]
	v_cvt_pk_bf16_f32 v4, v4, v5
	v_cvt_pk_bf16_f32 v5, v6, v7
	ds_write2_b64 v0, v[2:3], v[4:5] offset0:204 offset1:206
	v_and_b32_e32 v0, 0x70, v145
	v_mul_u32_u24_e32 v2, 0x90, v8
	v_add3_u32 v12, v47, v0, v2
	ds_read_b128 v[2:5], v12
	v_lshl_add_u64 v[6:7], v[14:15], 0, v[0:1]
	v_mul_u32_u24_e32 v0, 0x60, v8
	v_lshlrev_b32_e32 v0, 1, v0
	v_lshl_add_u64 v[8:9], v[6:7], 0, v[0:1]
	s_waitcnt lgkmcnt(0)
	global_store_dwordx4 v[8:9], v[2:5], off
	ds_read_b128 v[2:5], v12 offset:1152
	v_lshl_add_u64 v[10:11], v[8:9], 0, s[2:3]
	s_waitcnt lgkmcnt(0)
	global_store_dwordx4 v[8:9], v[2:5], off offset:1536
	ds_read_b128 v[2:5], v12 offset:2304
	s_waitcnt lgkmcnt(0)
	global_store_dwordx4 v[8:9], v[2:5], off offset:3072
	ds_read_b128 v[2:5], v12 offset:3456
	v_or_b32_e32 v8, 0x1800, v0
	v_mov_b32_e32 v9, v1
	v_lshl_add_u64 v[8:9], v[6:7], 0, v[8:9]
	s_waitcnt lgkmcnt(0)
	global_store_dwordx4 v[10:11], v[2:5], off offset:3072
	ds_read_b128 v[2:5], v12 offset:4608
	s_waitcnt lgkmcnt(0)
	global_store_dwordx4 v[8:9], v[2:5], off
	ds_read_b128 v[2:5], v12 offset:5760
	v_add_u32_e32 v8, 0x1e00, v0
	v_mov_b32_e32 v9, v1
	v_lshl_add_u64 v[8:9], v[6:7], 0, v[8:9]
	s_waitcnt lgkmcnt(0)
	global_store_dwordx4 v[8:9], v[2:5], off
	ds_read_b128 v[2:5], v12 offset:6912
	v_add_u32_e32 v8, 0x2400, v0
	v_mov_b32_e32 v9, v1
	v_lshl_add_u64 v[8:9], v[6:7], 0, v[8:9]
	s_waitcnt lgkmcnt(0)
	global_store_dwordx4 v[8:9], v[2:5], off
	ds_read_b128 v[2:5], v12 offset:8064
	v_add_u32_e32 v8, 0x2a00, v0
	v_mov_b32_e32 v9, v1
	v_lshl_add_u64 v[8:9], v[6:7], 0, v[8:9]
	s_waitcnt lgkmcnt(0)
	global_store_dwordx4 v[8:9], v[2:5], off
	ds_read_b128 v[2:5], v12 offset:9216
	v_or_b32_e32 v8, 0x3000, v0
	v_mov_b32_e32 v9, v1
	v_lshl_add_u64 v[8:9], v[6:7], 0, v[8:9]
	s_waitcnt lgkmcnt(0)
	global_store_dwordx4 v[8:9], v[2:5], off
	ds_read_b128 v[2:5], v12 offset:10368
	v_add_u32_e32 v8, 0x3600, v0
	v_mov_b32_e32 v9, v1
	v_lshl_add_u64 v[8:9], v[6:7], 0, v[8:9]
	s_waitcnt lgkmcnt(0)
	global_store_dwordx4 v[8:9], v[2:5], off
	ds_read_b128 v[2:5], v12 offset:11520
	v_add_u32_e32 v8, 0x3c00, v0
	v_mov_b32_e32 v9, v1
	v_lshl_add_u64 v[8:9], v[6:7], 0, v[8:9]
	s_waitcnt lgkmcnt(0)
	global_store_dwordx4 v[8:9], v[2:5], off
	ds_read_b128 v[2:5], v12 offset:12672
	v_add_u32_e32 v8, 0x4200, v0
	v_mov_b32_e32 v9, v1
	v_lshl_add_u64 v[8:9], v[6:7], 0, v[8:9]
	s_waitcnt lgkmcnt(0)
	global_store_dwordx4 v[8:9], v[2:5], off
	ds_read_b128 v[2:5], v12 offset:13824
	v_or_b32_e32 v8, 0x4800, v0
	v_mov_b32_e32 v9, v1
	v_lshl_add_u64 v[8:9], v[6:7], 0, v[8:9]
	s_waitcnt lgkmcnt(0)
	global_store_dwordx4 v[8:9], v[2:5], off
	ds_read_b128 v[2:5], v12 offset:14976
	v_add_u32_e32 v8, 0x4e00, v0
	v_mov_b32_e32 v9, v1
	v_lshl_add_u64 v[8:9], v[6:7], 0, v[8:9]
	s_waitcnt lgkmcnt(0)
	global_store_dwordx4 v[8:9], v[2:5], off
	ds_read_b128 v[2:5], v12 offset:16128
	v_add_u32_e32 v8, 0x5400, v0
	v_mov_b32_e32 v9, v1
	v_lshl_add_u64 v[8:9], v[6:7], 0, v[8:9]
	v_add_u32_e32 v0, 0x5a00, v0
	s_waitcnt lgkmcnt(0)
	global_store_dwordx4 v[8:9], v[2:5], off
	ds_read_b128 v[2:5], v12 offset:17280
	v_lshl_add_u64 v[6:7], v[6:7], 0, v[0:1]
	s_waitcnt lgkmcnt(0)
	global_store_dwordx4 v[6:7], v[2:5], off
	s_branch .LBB0_709
